# v44 plus NA attention score pass: branch-free batched relative-position-bias lookup (4 ds_read + one wait + v_cndmask per tile instead of 4 exec-masked cores)
# speedup vs baseline: 1.0056x; 1.0056x over previous
; #define LAS __attribute__((address_space(3)))
; #define NA_DECODE(u_, b, h, rbase, hc, krlo, nkr) do { hc = (u_) & 1; const int rg_ = ((u_) >> 1) & 7; h = ((u_) >> 4) & 15; b = (u_) >> 8; rbase = 4 * rg_; \
;                     krlo = min(max(rbase - 4, 0), 24); nkr = min(max(rbase - 1, 0), 24) + 8 - krlo; } while (0)
; template <int L>
; __device__ __forceinline__ void layer_body(const Args& args, LAS unsigned char* lds, const int wave, const int G, const int gw, const int NGW, const int lo, const int hi,
;                                            unsigned char* const ws_kernel, const XcdBarrier& bar, int& pid) {
;     ...
;                 int unit = vcu;
;                 { const int qi = lane & 15, kg = lane >> 4, sch = tid & 15, skey = tid >> 4; if (unit < UEND) { NA_LOADROWS(unit, rst, D); NA_LOADQ(unit); } }
;                 for (; unit < UEND; unit += GH) {
;                     int b, h, rbase, hc, krlo, nkr; NA_DECODE(unit, b, h, rbase, hc, krlo, nkr);
;                     int tl_ = tid; asm volatile("" : "+v"(tl_));
;                     const int lane = tl_ & 63, qi = lane & 15, kg = lane >> 4, sch = tl_ & 15, skey = tl_ >> 4;
; #pragma unroll
;                     for (int i = 0; i < 14; ++i) { const int kid = skey + 32 * i; *(LAS v4u*)(size_t)(IMG + kid * KPITCH + 16 * sch) = rst[i]; }
;                     if (tl_ < 15 * 31) rl[tl_] = rpb[h * 15 * 31 + tl_];
;                     __syncthreads();
;                     NA_LOADROWS(unit, rst, 2 * D);
.LBB0_846:
	s_or_b64 exec, exec, s[0:1]
	s_add_i32 s0, s81, s84
	s_and_b32 s14, s0, 28
	s_max_u32 s0, s14, 4
	v_med3_u32 v0, s14, 1, 25
	v_add_u32_e32 v4, 32, v77
	v_add_u32_e32 v8, 64, v77
	v_add_u32_e32 v12, 0x60, v77
	v_add_u32_e32 v16, 0x80, v77
	v_add_u32_e32 v20, 0xa0, v77
	v_add_u32_e32 v40, 0xc0, v77
	v_add_u32_e32 v44, 0xe0, v77
	v_add_u32_e32 v48, 0x100, v77
	v_add_u32_e32 v52, 0x120, v77
	v_add_u32_e32 v56, 0x140, v77
	v_add_u32_e32 v60, 0x160, v77
	v_add_u32_e32 v64, 0x180, v77
	v_add_u32_e32 v70, 0x1a0, v77
	s_and_b32 s1, s21, 1
	s_lshl_b32 s6, s36, 8
	v_subrev_u32_e32 v0, s0, v0
	s_add_u32 s6, s57, s6
	v_add_u32_e32 v72, 10, v0
	v_mul_hi_i32 v0, v77, s9
	v_mul_hi_i32 v5, v4, s9
	v_mul_hi_i32 v9, v8, s9
	v_mul_hi_i32 v13, v12, s9
	v_mul_hi_i32 v17, v16, s9
	v_mul_hi_i32 v21, v20, s9
	v_mul_hi_i32 v41, v40, s9
	v_mul_hi_i32 v45, v44, s9
	v_mul_hi_i32 v49, v48, s9
	v_mul_hi_i32 v53, v52, s9
	v_mul_hi_i32 v57, v56, s9
	v_mul_hi_i32 v61, v60, s9
	v_mul_hi_i32 v65, v64, s9
	v_mul_hi_i32 v73, v70, s9
	s_addc_u32 s7, s58, 0
	v_lshrrev_b32_e32 v1, 31, v0
	v_ashrrev_i32_e32 v0, 4, v0
	v_lshrrev_b32_e32 v6, 31, v5
	v_ashrrev_i32_e32 v5, 4, v5
	v_lshrrev_b32_e32 v10, 31, v9
	v_ashrrev_i32_e32 v9, 4, v9
	v_lshrrev_b32_e32 v14, 31, v13
	v_ashrrev_i32_e32 v13, 4, v13
	v_lshrrev_b32_e32 v18, 31, v17
	v_ashrrev_i32_e32 v17, 4, v17
	v_lshrrev_b32_e32 v22, 31, v21
	v_ashrrev_i32_e32 v21, 4, v21
	v_lshrrev_b32_e32 v42, 31, v41
	v_ashrrev_i32_e32 v41, 4, v41
	v_lshrrev_b32_e32 v46, 31, v45
	v_ashrrev_i32_e32 v45, 4, v45
	v_lshrrev_b32_e32 v50, 31, v49
	v_ashrrev_i32_e32 v49, 4, v49
	v_lshrrev_b32_e32 v54, 31, v53
	v_ashrrev_i32_e32 v53, 4, v53
	v_lshrrev_b32_e32 v58, 31, v57
	v_ashrrev_i32_e32 v57, 4, v57
	v_lshrrev_b32_e32 v62, 31, v61
	v_ashrrev_i32_e32 v61, 4, v61
	v_lshrrev_b32_e32 v66, 31, v65
	v_ashrrev_i32_e32 v65, 4, v65
	v_lshrrev_b32_e32 v74, 31, v73
	v_ashrrev_i32_e32 v73, 4, v73
	v_lshl_add_u64 v[68:69], s[6:7], 0, v[104:105]
	s_add_i32 s6, s85, s96
	v_add_u32_e32 v78, v0, v1
	v_add_u32_e32 v80, v5, v6
	v_add_u32_e32 v82, v9, v10
	v_add_u32_e32 v84, v13, v14
	v_add_u32_e32 v86, v17, v18
	v_add_u32_e32 v88, v21, v22
	v_add_u32_e32 v90, v41, v42
	v_add_u32_e32 v92, v45, v46
	v_add_u32_e32 v94, v49, v50
	v_add_u32_e32 v96, v53, v54
	v_add_u32_e32 v98, v57, v58
	v_add_u32_e32 v100, v61, v62
	v_add_u32_e32 v102, v65, v66
	v_add_u32_e32 v113, v73, v74
	v_sub_u32_e64 v71, s14, 4 clamp
	s_and_b32 s60, s6, 0xfffff800
	s_mul_i32 s6, s1, 24
	v_min_i32_e32 v0, v78, v72
	v_min_i32_e32 v5, v80, v72
	v_min_i32_e32 v9, v82, v72
	v_min_i32_e32 v13, v84, v72
	v_min_i32_e32 v17, v86, v72
	v_min_i32_e32 v21, v88, v72
	v_min_i32_e32 v41, v90, v72
	v_min_i32_e32 v45, v92, v72
	v_min_i32_e32 v49, v94, v72
	v_min_i32_e32 v53, v96, v72
	v_min_i32_e32 v57, v98, v72
	v_min_i32_e32 v61, v100, v72
	v_min_i32_e32 v65, v102, v72
	v_min_i32_e32 v72, v113, v72
	s_or_b32 s8, s60, s6
	v_add_lshl_u32 v0, v0, v71, 6
	v_mad_i32_i24 v79, v78, s88, v77
	v_add_lshl_u32 v5, v5, v71, 6
	v_mad_i32_i24 v81, v80, s88, v4
	v_add_lshl_u32 v9, v9, v71, 6
	v_mad_i32_i24 v83, v82, s88, v8
	v_add_lshl_u32 v13, v13, v71, 6
	v_mad_i32_i24 v85, v84, s88, v12
	v_add_lshl_u32 v17, v17, v71, 6
	v_mad_i32_i24 v87, v86, s88, v16
	v_add_lshl_u32 v21, v21, v71, 6
	v_mad_i32_i24 v89, v88, s88, v20
	v_add_lshl_u32 v41, v41, v71, 6
	v_mad_i32_i24 v91, v90, s88, v40
	v_add_lshl_u32 v45, v45, v71, 6
	v_mad_i32_i24 v93, v92, s88, v44
	v_add_lshl_u32 v49, v49, v71, 6
	v_mad_i32_i24 v95, v94, s88, v48
	v_add_lshl_u32 v53, v53, v71, 6
	v_mad_i32_i24 v97, v96, s88, v52
	v_add_lshl_u32 v57, v57, v71, 6
	v_mad_i32_i24 v99, v98, s88, v56
	v_add_lshl_u32 v61, v61, v71, 6
	v_mad_i32_i24 v101, v100, s88, v60
	v_add_lshl_u32 v65, v65, v71, 6
	v_mad_i32_i24 v103, v102, s88, v64
	v_add_lshl_u32 v71, v72, v71, 6
	v_mad_i32_i24 v114, v113, s88, v70
	v_add3_u32 v0, v79, s8, v0
	v_add3_u32 v4, v81, s8, v5
	v_add3_u32 v8, v83, s8, v9
	v_add3_u32 v12, v85, s8, v13
	v_add3_u32 v16, v87, s8, v17
	v_add3_u32 v20, v89, s8, v21
	v_add3_u32 v40, v91, s8, v41
	v_add3_u32 v44, v93, s8, v45
	v_add3_u32 v48, v95, s8, v49
	v_add3_u32 v52, v97, s8, v53
	v_add3_u32 v56, v99, s8, v57
	v_add3_u32 v60, v101, s8, v61
	v_add3_u32 v64, v103, s8, v65
	v_add3_u32 v70, v114, s8, v71
	v_mad_i64_i32 v[0:1], s[6:7], v0, s22, v[68:69]
	v_mad_i64_i32 v[4:5], s[6:7], v4, s22, v[68:69]
	v_mad_i64_i32 v[8:9], s[6:7], v8, s22, v[68:69]
	v_mad_i64_i32 v[12:13], s[6:7], v12, s22, v[68:69]
	v_mad_i64_i32 v[16:17], s[6:7], v16, s22, v[68:69]
	v_mad_i64_i32 v[20:21], s[6:7], v20, s22, v[68:69]
	v_mad_i64_i32 v[40:41], s[6:7], v40, s22, v[68:69]
	v_mad_i64_i32 v[44:45], s[6:7], v44, s22, v[68:69]
	v_mad_i64_i32 v[48:49], s[6:7], v48, s22, v[68:69]
	v_mad_i64_i32 v[52:53], s[6:7], v52, s22, v[68:69]
	v_mad_i64_i32 v[56:57], s[6:7], v56, s22, v[68:69]
	v_mad_i64_i32 v[60:61], s[6:7], v60, s22, v[68:69]
	v_mad_i64_i32 v[64:65], s[6:7], v64, s22, v[68:69]
	v_mad_i64_i32 v[68:69], s[6:7], v70, s22, v[68:69]
	s_waitcnt lgkmcnt(0)
	s_barrier
; #define LAS __attribute__((address_space(3)))
; template <int L>
; __device__ __forceinline__ void layer_body(const Args& args, LAS unsigned char* lds, const int wave, const int G, const int gw, const int NGW, const int lo, const int hi,
;                                            unsigned char* const ws_kernel, const XcdBarrier& bar, int& pid) {
;     ...
;                     NA_LOADROWS(unit, rst, 2 * D);
;                     const int rr = wave >> 1, cb = 2 * hc + (wave & 1), r = rbase + rr, r0w = min(max(r - 4, 0), 24), cs = min(max(16 * cb - 8, 0), 32), coloff = cs - 24 * hc;
;                     const int c = 16 * cb + qi, wsq = min(max(c - 8, 0), 48);
;                     f32x4 sc[16];
; #pragma unroll
;                     for (int t = 0; t < 16; ++t) {
;                         const int irow = (r0w - krlo + (t >> 1)) * 40 + coloff + 16 * (t & 1);
;                         const unsigned ka = IMG + (unsigned)((irow + qi) * KPITCH + 16 * kg);
;                         f32x4 a = (f32x4){0.f, 0.f, 0.f, 0.f};
; #pragma unroll
;                         for (int ks = 0; ks < 4; ++ks) a = __builtin_amdgcn_mfma_f32_16x16x32_bf16(*(const LAS bf16x8*)(size_t)(ka + 64 * ks), qfn[ks], a, 0, 0, 0);
;                         const int dr = r0w + (t >> 1) - r + 7;
; #pragma unroll
;                         for (int j = 0; j < 4; ++j) { const int kc = cs + 16 * (t & 1) + 4 * kg + j; const bool valid = (kc >= wsq) && (kc < wsq + 16); const int dc = min(max(kc - c + 15, 0), 30);
;                             sc[t][j] = valid ? a[j] * scale_log2 + rl[dr * 31 + dc] * LOG2E : -1e30f; }
	global_load_dwordx4 v[0:3], v[0:1], off
	s_add_i32 s14, s14, s53
	global_load_dwordx4 v[4:7], v[4:5], off
	s_lshl_b32 s7, s1, 5
	global_load_dwordx4 v[8:11], v[8:9], off
	s_max_i32 s6, s14, 4
	global_load_dwordx4 v[12:15], v[12:13], off
	s_or_b32 s7, s7, s54
	global_load_dwordx4 v[16:19], v[16:17], off
	s_add_i32 s6, s6, -4
	global_load_dwordx4 v[20:23], v[20:21], off
	s_max_i32 s8, s7, 8
	global_load_dwordx4 v[40:43], v[40:41], off
	s_min_u32 s6, s6, 24
	global_load_dwordx4 v[44:47], v[44:45], off
	s_add_i32 s8, s8, -8
	global_load_dwordx4 v[48:51], v[48:49], off
	s_min_u32 s8, s8, 32
	global_load_dwordx4 v[52:55], v[52:53], off
	s_mulk_i32 s1, 0xffe8
	global_load_dwordx4 v[56:59], v[56:57], off
	v_or_b32_e32 v109, s7, v112
	global_load_dwordx4 v[60:63], v[60:61], off
	s_sub_i32 s41, s6, s0
	global_load_dwordx4 v[64:67], v[64:65], off
	s_add_i32 s15, s8, s1
	global_load_dwordx4 v[68:71], v[68:69], off
	v_max_i32_e32 v72, 8, v109
	s_mul_i32 s41, s41, 40
	v_bfe_u32 v76, v111, 4, 2
	v_add_u32_e32 v72, -8, v72
	v_add_u32_e32 v121, s15, v112
	s_sub_i32 s0, s6, s14
	s_add_i32 s6, s41, 0xa0
	v_min_u32_e32 v129, 48, v72
	v_lshl_add_u32 v118, v76, 4, 0
	v_add_u32_e32 v72, s6, v121
	v_mad_i32_i24 v104, v72, s90, v118
	ds_read_b128 v[72:75], v104
	ds_read_b128 v[122:125], v104 offset:64
	s_waitcnt lgkmcnt(1)
	v_mfma_f32_16x16x32_bf16 v[72:75], v[72:75], v[24:27], 0
	v_lshlrev_b32_e32 v110, 2, v76
	v_add_u32_e32 v134, s8, v110
	v_add_u32_e32 v131, 16, v129
	s_waitcnt lgkmcnt(0)
	v_mfma_f32_16x16x32_bf16 v[72:75], v[122:125], v[28:31], v[72:75]
	ds_read_b128 v[122:125], v104 offset:128
	s_mulk_i32 s0, 0x7c
	s_add_i32 s42, s0, 0
	s_waitcnt lgkmcnt(0)
	v_mfma_f32_16x16x32_bf16 v[72:75], v[122:125], v[32:35], v[72:75]
	ds_read_b128 v[122:125], v104 offset:192
	v_cmp_ge_u32_e32 vcc, v134, v129
	v_cmp_lt_u32_e64 s[0:1], v134, v131
	s_waitcnt lgkmcnt(0)
	v_mfma_f32_16x16x32_bf16 v[72:75], v[122:125], v[36:39], v[72:75]
	v_sub_u32_e32 v115, v134, v109
	s_add_i32 s42, s42, 0x1dc00
	s_and_b64 s[64:65], vcc, s[0:1]
	v_mov_b32_e32 v104, 0xf149f2ca
	v_max_i32_e32 v124, -15, v115
	v_mov_b32_e32 v115, 0xf149f2ca
	v_mov_b32_e32 v204, 0xf149f2ca
	s_nop 1
	v_add_u32_e32 v201, 15, v124
	v_min_u32_e32 v201, 30, v201
	v_lshl_add_u32 v216, v201, 2, s42
	ds_read_b32 v201, v216 offset:868
	v_mov_b32_e32 v200, v72
	s_waitcnt lgkmcnt(0)
	v_pk_mul_f32 v[200:201], v[200:201], s[62:63]
	s_nop 0
	v_add_f32_e32 v200, v200, v201
	v_cndmask_b32_e64 v115, v204, v200, s[64:65]
	v_or_b32_e32 v72, 1, v134
	v_cmp_ge_u32_e32 vcc, v72, v129
	v_cmp_lt_u32_e64 s[0:1], v72, v131
	v_sub_u32_e32 v72, v72, v109
	s_and_b64 s[66:67], vcc, s[0:1]
	v_max_i32_e32 v125, -15, v72
	s_nop 1
	v_add_u32_e32 v203, 15, v125
	v_min_u32_e32 v203, 30, v203
	v_lshl_add_u32 v217, v203, 2, s42
	ds_read_b32 v203, v217 offset:868
	v_mov_b32_e32 v202, v73
	s_waitcnt lgkmcnt(0)
	v_pk_mul_f32 v[202:203], v[202:203], s[62:63]
	s_nop 0
	v_add_f32_e32 v202, v202, v203
	v_cndmask_b32_e64 v104, v204, v202, s[66:67]
	v_or_b32_e32 v72, 2, v134
	v_cmp_ge_u32_e32 vcc, v72, v129
	v_cmp_lt_u32_e64 s[0:1], v72, v131
	v_sub_u32_e32 v72, v72, v109
	s_and_b64 s[68:69], vcc, s[0:1]
	v_mov_b32_e32 v116, 0xf149f2ca
	v_max_i32_e32 v126, -15, v72
	v_mov_b32_e32 v117, 0xf149f2ca
	s_nop 1
	v_add_u32_e32 v213, 15, v126
	v_min_u32_e32 v213, 30, v213
	v_lshl_add_u32 v218, v213, 2, s42
	ds_read_b32 v213, v218 offset:868
	v_mov_b32_e32 v212, v74
	s_waitcnt lgkmcnt(0)
	v_pk_mul_f32 v[212:213], v[212:213], s[62:63]
	s_nop 0
	v_add_f32_e32 v212, v212, v213
	v_cndmask_b32_e64 v117, v204, v212, s[68:69]
	v_or_b32_e32 v72, 3, v134
	v_cmp_ge_u32_e32 vcc, v72, v129
	v_cmp_lt_u32_e64 s[0:1], v72, v131
	v_sub_u32_e32 v72, v72, v109
	s_and_b64 s[70:71], vcc, s[0:1]
	v_max_i32_e32 v127, -15, v72
	s_nop 1
	v_add_u32_e32 v215, 15, v127
	v_min_u32_e32 v215, 30, v215
	v_lshl_add_u32 v219, v215, 2, s42
	ds_read_b32 v215, v219 offset:868
	v_mov_b32_e32 v214, v75
	s_waitcnt lgkmcnt(0)
	v_pk_mul_f32 v[214:215], v[214:215], s[62:63]
	s_nop 0
	v_add_f32_e32 v214, v214, v215
	v_cndmask_b32_e64 v116, v204, v214, s[70:71]
	v_add_u32_e32 v128, 16, v121
	v_add_u32_e32 v72, s6, v128
	v_mad_i32_i24 v119, v72, s90, v118
	ds_read_b128 v[72:75], v119
	ds_read_b128 v[136:139], v119 offset:64
	v_add_u32_e32 v120, 16, v134
	v_cmp_ge_u32_e32 vcc, v120, v129
	v_cmp_lt_u32_e64 s[0:1], v134, v129
	v_sub_u32_e32 v120, v120, v109
	s_and_b64 s[72:73], vcc, s[0:1]
	v_max_i32_e32 v130, -15, v120
	v_mov_b32_e32 v120, 0xf149f2ca
	s_waitcnt lgkmcnt(1)
	v_mfma_f32_16x16x32_bf16 v[72:75], v[72:75], v[24:27], 0
	s_waitcnt lgkmcnt(0)
	v_mfma_f32_16x16x32_bf16 v[72:75], v[136:139], v[28:31], v[72:75]
	ds_read_b128 v[136:139], v119 offset:128
	s_waitcnt lgkmcnt(0)
	v_mfma_f32_16x16x32_bf16 v[72:75], v[136:139], v[32:35], v[72:75]
	ds_read_b128 v[136:139], v119 offset:192
	v_mov_b32_e32 v119, 0xf149f2ca
	s_waitcnt lgkmcnt(0)
	v_mfma_f32_16x16x32_bf16 v[72:75], v[136:139], v[36:39], v[72:75]
	s_nop 1
	v_add_u32_e32 v201, 15, v130
	v_min_u32_e32 v201, 30, v201
	v_lshl_add_u32 v220, v201, 2, s42
	ds_read_b32 v201, v220 offset:868
	s_nop 1
	v_mov_b32_e32 v200, v72
	s_waitcnt lgkmcnt(0)
	v_pk_mul_f32 v[200:201], v[200:201], s[62:63]
	s_nop 0
	v_add_f32_e32 v200, v200, v201
	v_cndmask_b32_e64 v120, v204, v200, s[72:73]
	s_nop 4
	v_add_u32_e32 v72, 17, v134
	v_cmp_ge_u32_e32 vcc, v72, v129
	v_cmp_lt_u32_e64 s[0:1], v72, v131
	v_sub_u32_e32 v72, v72, v109
	s_and_b64 s[74:75], vcc, s[0:1]
	v_max_i32_e32 v132, -15, v72
	s_nop 1
	v_add_u32_e32 v203, 15, v132
	v_min_u32_e32 v203, 30, v203
	v_lshl_add_u32 v221, v203, 2, s42
	ds_read_b32 v203, v221 offset:868
	v_mov_b32_e32 v202, v73
	s_waitcnt lgkmcnt(0)
; #define LAS __attribute__((address_space(3)))
; template <int L>
; __device__ __forceinline__ void layer_body(const Args& args, LAS unsigned char* lds, const int wave, const int G, const int gw, const int NGW, const int lo, const int hi,
;                                            unsigned char* const ws_kernel, const XcdBarrier& bar, int& pid) {
;     ...
;                     f32x4 sc[16];
; #pragma unroll
;                     for (int t = 0; t < 16; ++t) {
;                         const int irow = (r0w - krlo + (t >> 1)) * 40 + coloff + 16 * (t & 1);
;                         const unsigned ka = IMG + (unsigned)((irow + qi) * KPITCH + 16 * kg);
;                         f32x4 a = (f32x4){0.f, 0.f, 0.f, 0.f};
; #pragma unroll
;                         for (int ks = 0; ks < 4; ++ks) a = __builtin_amdgcn_mfma_f32_16x16x32_bf16(*(const LAS bf16x8*)(size_t)(ka + 64 * ks), qfn[ks], a, 0, 0, 0);
;                         const int dr = r0w + (t >> 1) - r + 7;
; #pragma unroll
;                         for (int j = 0; j < 4; ++j) { const int kc = cs + 16 * (t & 1) + 4 * kg + j; const bool valid = (kc >= wsq) && (kc < wsq + 16); const int dc = min(max(kc - c + 15, 0), 30);
;                             sc[t][j] = valid ? a[j] * scale_log2 + rl[dr * 31 + dc] * LOG2E : -1e30f; }
	v_pk_mul_f32 v[202:203], v[202:203], s[62:63]
	s_nop 0
	v_add_f32_e32 v202, v202, v203
	v_cndmask_b32_e64 v119, v204, v202, s[74:75]
	v_add_u32_e32 v72, 18, v134
	v_cmp_ge_u32_e32 vcc, v72, v129
	v_cmp_lt_u32_e64 s[0:1], v72, v131
	v_sub_u32_e32 v72, v72, v109
	s_and_b64 s[76:77], vcc, s[0:1]
	v_mov_b32_e32 v122, 0xf149f2ca
	v_max_i32_e32 v133, -15, v72
	v_mov_b32_e32 v123, 0xf149f2ca
	s_nop 1
	v_add_u32_e32 v213, 15, v133
	v_min_u32_e32 v213, 30, v213
	v_lshl_add_u32 v222, v213, 2, s42
	ds_read_b32 v213, v222 offset:868
	v_mov_b32_e32 v212, v74
	s_waitcnt lgkmcnt(0)
	v_pk_mul_f32 v[212:213], v[212:213], s[62:63]
	s_nop 0
	v_add_f32_e32 v212, v212, v213
	v_cndmask_b32_e64 v123, v204, v212, s[76:77]
	v_add_u32_e32 v72, 19, v134
	v_cmp_ge_u32_e32 vcc, v72, v129
	v_cmp_lt_u32_e64 s[0:1], v72, v131
	v_sub_u32_e32 v72, v72, v109
	s_and_b64 s[0:1], vcc, s[0:1]
	v_max_i32_e32 v134, -15, v72
	s_nop 1
	v_add_u32_e32 v215, 15, v134
	v_min_u32_e32 v215, 30, v215
	v_lshl_add_u32 v223, v215, 2, s42
	ds_read_b32 v215, v223 offset:868
	v_mov_b32_e32 v214, v75
	s_waitcnt lgkmcnt(0)
	v_pk_mul_f32 v[214:215], v[214:215], s[62:63]
	s_nop 0
	v_add_f32_e32 v214, v214, v215
	v_cndmask_b32_e64 v122, v204, v214, s[0:1]
	s_add_i32 s7, s41, 0xc8
	v_add_u32_e32 v72, s7, v121
	v_mad_i32_i24 v129, v72, s90, v118
	ds_read_b128 v[72:75], v129
	ds_read_b128 v[136:139], v129 offset:64
	v_mov_b32_e32 v131, 0xf149f2ca
	s_waitcnt lgkmcnt(1)
	v_mfma_f32_16x16x32_bf16 v[72:75], v[72:75], v[24:27], 0
	s_waitcnt lgkmcnt(0)
	v_mfma_f32_16x16x32_bf16 v[72:75], v[136:139], v[28:31], v[72:75]
	ds_read_b128 v[136:139], v129 offset:128
	s_waitcnt lgkmcnt(0)
	v_mfma_f32_16x16x32_bf16 v[72:75], v[136:139], v[32:35], v[72:75]
	ds_read_b128 v[136:139], v129 offset:192
	v_mov_b32_e32 v129, 0xf149f2ca
	s_waitcnt lgkmcnt(0)
	v_mfma_f32_16x16x32_bf16 v[72:75], v[136:139], v[36:39], v[72:75]
	ds_read_b32 v201, v216 offset:992
	ds_read_b32 v203, v217 offset:992
	ds_read_b32 v213, v218 offset:992
	ds_read_b32 v215, v219 offset:992
	s_nop 4
	v_mov_b32_e32 v200, v72
	v_mov_b32_e32 v202, v73
	v_mov_b32_e32 v212, v74
	v_mov_b32_e32 v214, v75
	s_waitcnt lgkmcnt(0)
	v_pk_mul_f32 v[200:201], v[200:201], s[62:63]
	v_pk_mul_f32 v[202:203], v[202:203], s[62:63]
	v_pk_mul_f32 v[212:213], v[212:213], s[62:63]
	v_pk_mul_f32 v[214:215], v[214:215], s[62:63]
	v_add_f32_e32 v200, v200, v201
	v_add_f32_e32 v202, v202, v203
	v_add_f32_e32 v212, v212, v213
	v_add_f32_e32 v214, v214, v215
	v_cndmask_b32_e64 v131, v204, v200, s[64:65]
	v_cndmask_b32_e64 v129, v204, v202, s[66:67]
	v_cndmask_b32_e64 v136, v204, v212, s[68:69]
	v_cndmask_b32_e64 v135, v204, v214, s[70:71]
	v_add_u32_e32 v72, s7, v128
	v_mad_i32_i24 v137, v72, s90, v118
	ds_read_b128 v[72:75], v137
	ds_read_b128 v[138:141], v137 offset:64
	s_waitcnt lgkmcnt(1)
	v_mfma_f32_16x16x32_bf16 v[72:75], v[72:75], v[24:27], 0
	s_waitcnt lgkmcnt(0)
	v_mfma_f32_16x16x32_bf16 v[72:75], v[138:141], v[28:31], v[72:75]
	ds_read_b128 v[138:141], v137 offset:128
	s_waitcnt lgkmcnt(0)
	v_mfma_f32_16x16x32_bf16 v[72:75], v[138:141], v[32:35], v[72:75]
	ds_read_b128 v[138:141], v137 offset:192
	v_mov_b32_e32 v137, 0xf149f2ca
	s_waitcnt lgkmcnt(0)
	v_mfma_f32_16x16x32_bf16 v[72:75], v[138:141], v[36:39], v[72:75]
	v_mov_b32_e32 v138, 0xf149f2ca
	ds_read_b32 v201, v220 offset:992
	ds_read_b32 v203, v221 offset:992
	ds_read_b32 v213, v222 offset:992
	ds_read_b32 v215, v223 offset:992
	s_nop 4
	v_mov_b32_e32 v200, v72
	v_mov_b32_e32 v202, v73
	v_mov_b32_e32 v212, v74
	v_mov_b32_e32 v214, v75
	s_waitcnt lgkmcnt(0)
	v_pk_mul_f32 v[200:201], v[200:201], s[62:63]
	v_pk_mul_f32 v[202:203], v[202:203], s[62:63]
	v_pk_mul_f32 v[212:213], v[212:213], s[62:63]
	v_pk_mul_f32 v[214:215], v[214:215], s[62:63]
	v_add_f32_e32 v200, v200, v201
	v_add_f32_e32 v202, v202, v203
	v_add_f32_e32 v212, v212, v213
	v_add_f32_e32 v214, v214, v215
	v_cndmask_b32_e64 v138, v204, v200, s[72:73]
	v_cndmask_b32_e64 v137, v204, v202, s[74:75]
	v_cndmask_b32_e64 v140, v204, v212, s[76:77]
	v_cndmask_b32_e64 v139, v204, v214, s[0:1]
	s_add_i32 s8, s41, 0xf0
	v_add_u32_e32 v72, s8, v121
	v_mad_i32_i24 v141, v72, s90, v118
	ds_read_b128 v[72:75], v141
	ds_read_b128 v[142:145], v141 offset:64
	s_waitcnt lgkmcnt(1)
	v_mfma_f32_16x16x32_bf16 v[72:75], v[72:75], v[24:27], 0
	s_waitcnt lgkmcnt(0)
	v_mfma_f32_16x16x32_bf16 v[72:75], v[142:145], v[28:31], v[72:75]
	ds_read_b128 v[142:145], v141 offset:128
	s_waitcnt lgkmcnt(0)
	v_mfma_f32_16x16x32_bf16 v[72:75], v[142:145], v[32:35], v[72:75]
	ds_read_b128 v[142:145], v141 offset:192
	v_mov_b32_e32 v141, 0xf149f2ca
	s_waitcnt lgkmcnt(0)
	v_mfma_f32_16x16x32_bf16 v[72:75], v[142:145], v[36:39], v[72:75]
	v_mov_b32_e32 v142, 0xf149f2ca
	ds_read_b32 v201, v216 offset:1116
	ds_read_b32 v203, v217 offset:1116
	ds_read_b32 v213, v218 offset:1116
	ds_read_b32 v215, v219 offset:1116
	s_nop 4
	v_mov_b32_e32 v200, v72
	v_mov_b32_e32 v202, v73
	v_mov_b32_e32 v212, v74
	v_mov_b32_e32 v214, v75
	s_waitcnt lgkmcnt(0)
	v_pk_mul_f32 v[200:201], v[200:201], s[62:63]
	v_pk_mul_f32 v[202:203], v[202:203], s[62:63]
	v_pk_mul_f32 v[212:213], v[212:213], s[62:63]
	v_pk_mul_f32 v[214:215], v[214:215], s[62:63]
	v_add_f32_e32 v200, v200, v201
	v_add_f32_e32 v202, v202, v203
	v_add_f32_e32 v212, v212, v213
	v_add_f32_e32 v214, v214, v215
	v_cndmask_b32_e64 v142, v204, v200, s[64:65]
	v_cndmask_b32_e64 v141, v204, v202, s[66:67]
	v_cndmask_b32_e64 v144, v204, v212, s[68:69]
	v_cndmask_b32_e64 v143, v204, v214, s[70:71]
	v_add_u32_e32 v72, s8, v128
	v_mad_i32_i24 v145, v72, s90, v118
	ds_read_b128 v[72:75], v145
	ds_read_b128 v[146:149], v145 offset:64
	s_waitcnt lgkmcnt(1)
; #define LAS __attribute__((address_space(3)))
; template <int L>
; __device__ __forceinline__ void layer_body(const Args& args, LAS unsigned char* lds, const int wave, const int G, const int gw, const int NGW, const int lo, const int hi,
;                                            unsigned char* const ws_kernel, const XcdBarrier& bar, int& pid) {
;     ...
;                     f32x4 sc[16];
; #pragma unroll
;                     for (int t = 0; t < 16; ++t) {
;                         const int irow = (r0w - krlo + (t >> 1)) * 40 + coloff + 16 * (t & 1);
;                         const unsigned ka = IMG + (unsigned)((irow + qi) * KPITCH + 16 * kg);
;                         f32x4 a = (f32x4){0.f, 0.f, 0.f, 0.f};
; #pragma unroll
;                         for (int ks = 0; ks < 4; ++ks) a = __builtin_amdgcn_mfma_f32_16x16x32_bf16(*(const LAS bf16x8*)(size_t)(ka + 64 * ks), qfn[ks], a, 0, 0, 0);
;                         const int dr = r0w + (t >> 1) - r + 7;
; #pragma unroll
;                         for (int j = 0; j < 4; ++j) { const int kc = cs + 16 * (t & 1) + 4 * kg + j; const bool valid = (kc >= wsq) && (kc < wsq + 16); const int dc = min(max(kc - c + 15, 0), 30);
;                             sc[t][j] = valid ? a[j] * scale_log2 + rl[dr * 31 + dc] * LOG2E : -1e30f; }
	v_mfma_f32_16x16x32_bf16 v[72:75], v[72:75], v[24:27], 0
	s_waitcnt lgkmcnt(0)
	v_mfma_f32_16x16x32_bf16 v[72:75], v[146:149], v[28:31], v[72:75]
	ds_read_b128 v[146:149], v145 offset:128
	s_waitcnt lgkmcnt(0)
	v_mfma_f32_16x16x32_bf16 v[72:75], v[146:149], v[32:35], v[72:75]
	ds_read_b128 v[146:149], v145 offset:192
	v_mov_b32_e32 v145, 0xf149f2ca
	s_waitcnt lgkmcnt(0)
	v_mfma_f32_16x16x32_bf16 v[72:75], v[146:149], v[36:39], v[72:75]
	v_mov_b32_e32 v146, 0xf149f2ca
	ds_read_b32 v201, v220 offset:1116
	ds_read_b32 v203, v221 offset:1116
	ds_read_b32 v213, v222 offset:1116
	ds_read_b32 v215, v223 offset:1116
	s_nop 4
	v_mov_b32_e32 v200, v72
	v_mov_b32_e32 v202, v73
	v_mov_b32_e32 v212, v74
	v_mov_b32_e32 v214, v75
	s_waitcnt lgkmcnt(0)
	v_pk_mul_f32 v[200:201], v[200:201], s[62:63]
	v_pk_mul_f32 v[202:203], v[202:203], s[62:63]
	v_pk_mul_f32 v[212:213], v[212:213], s[62:63]
	v_pk_mul_f32 v[214:215], v[214:215], s[62:63]
	v_add_f32_e32 v200, v200, v201
	v_add_f32_e32 v202, v202, v203
	v_add_f32_e32 v212, v212, v213
	v_add_f32_e32 v214, v214, v215
	v_cndmask_b32_e64 v146, v204, v200, s[72:73]
	v_cndmask_b32_e64 v145, v204, v202, s[74:75]
	v_cndmask_b32_e64 v148, v204, v212, s[76:77]
	v_cndmask_b32_e64 v147, v204, v214, s[0:1]
	s_add_i32 s37, s41, 0x118
	v_add_u32_e32 v72, s37, v121
	v_mad_i32_i24 v149, v72, s90, v118
	ds_read_b128 v[72:75], v149
	ds_read_b128 v[150:153], v149 offset:64
	s_waitcnt lgkmcnt(1)
	v_mfma_f32_16x16x32_bf16 v[72:75], v[72:75], v[24:27], 0
	s_waitcnt lgkmcnt(0)
	v_mfma_f32_16x16x32_bf16 v[72:75], v[150:153], v[28:31], v[72:75]
	ds_read_b128 v[150:153], v149 offset:128
	s_waitcnt lgkmcnt(0)
	v_mfma_f32_16x16x32_bf16 v[72:75], v[150:153], v[32:35], v[72:75]
	ds_read_b128 v[150:153], v149 offset:192
	v_mov_b32_e32 v149, 0xf149f2ca
	s_waitcnt lgkmcnt(0)
	v_mfma_f32_16x16x32_bf16 v[72:75], v[150:153], v[36:39], v[72:75]
	v_mov_b32_e32 v150, 0xf149f2ca
	ds_read_b32 v201, v216 offset:1240
	ds_read_b32 v203, v217 offset:1240
	ds_read_b32 v213, v218 offset:1240
	ds_read_b32 v215, v219 offset:1240
	s_nop 4
	v_mov_b32_e32 v200, v72
	v_mov_b32_e32 v202, v73
	v_mov_b32_e32 v212, v74
	v_mov_b32_e32 v214, v75
	s_waitcnt lgkmcnt(0)
	v_pk_mul_f32 v[200:201], v[200:201], s[62:63]
	v_pk_mul_f32 v[202:203], v[202:203], s[62:63]
	v_pk_mul_f32 v[212:213], v[212:213], s[62:63]
	v_pk_mul_f32 v[214:215], v[214:215], s[62:63]
	v_add_f32_e32 v200, v200, v201
	v_add_f32_e32 v202, v202, v203
	v_add_f32_e32 v212, v212, v213
	v_add_f32_e32 v214, v214, v215
	v_cndmask_b32_e64 v150, v204, v200, s[64:65]
	v_cndmask_b32_e64 v149, v204, v202, s[66:67]
	v_cndmask_b32_e64 v152, v204, v212, s[68:69]
	v_cndmask_b32_e64 v151, v204, v214, s[70:71]
	v_add_u32_e32 v72, s37, v128
	v_mad_i32_i24 v153, v72, s90, v118
	ds_read_b128 v[72:75], v153
	ds_read_b128 v[154:157], v153 offset:64
	s_waitcnt lgkmcnt(1)
	v_mfma_f32_16x16x32_bf16 v[72:75], v[72:75], v[24:27], 0
	s_waitcnt lgkmcnt(0)
	v_mfma_f32_16x16x32_bf16 v[72:75], v[154:157], v[28:31], v[72:75]
	ds_read_b128 v[154:157], v153 offset:128
	s_waitcnt lgkmcnt(0)
	v_mfma_f32_16x16x32_bf16 v[72:75], v[154:157], v[32:35], v[72:75]
	ds_read_b128 v[154:157], v153 offset:192
	v_mov_b32_e32 v153, 0xf149f2ca
	s_waitcnt lgkmcnt(0)
	v_mfma_f32_16x16x32_bf16 v[72:75], v[154:157], v[36:39], v[72:75]
	v_mov_b32_e32 v154, 0xf149f2ca
	ds_read_b32 v201, v220 offset:1240
	ds_read_b32 v203, v221 offset:1240
	ds_read_b32 v213, v222 offset:1240
	ds_read_b32 v215, v223 offset:1240
	s_nop 4
	v_mov_b32_e32 v200, v72
	v_mov_b32_e32 v202, v73
	v_mov_b32_e32 v212, v74
	v_mov_b32_e32 v214, v75
	s_waitcnt lgkmcnt(0)
	v_pk_mul_f32 v[200:201], v[200:201], s[62:63]
	v_pk_mul_f32 v[202:203], v[202:203], s[62:63]
	v_pk_mul_f32 v[212:213], v[212:213], s[62:63]
	v_pk_mul_f32 v[214:215], v[214:215], s[62:63]
	v_add_f32_e32 v200, v200, v201
	v_add_f32_e32 v202, v202, v203
	v_add_f32_e32 v212, v212, v213
	v_add_f32_e32 v214, v214, v215
	v_cndmask_b32_e64 v154, v204, v200, s[72:73]
	v_cndmask_b32_e64 v153, v204, v202, s[74:75]
	v_cndmask_b32_e64 v156, v204, v212, s[76:77]
	v_cndmask_b32_e64 v155, v204, v214, s[0:1]
	s_add_i32 s38, s41, 0x140
	v_add_u32_e32 v72, s38, v121
	v_mad_i32_i24 v157, v72, s90, v118
	ds_read_b128 v[72:75], v157
	ds_read_b128 v[158:161], v157 offset:64
	s_waitcnt lgkmcnt(1)
	v_mfma_f32_16x16x32_bf16 v[72:75], v[72:75], v[24:27], 0
	s_waitcnt lgkmcnt(0)
	v_mfma_f32_16x16x32_bf16 v[72:75], v[158:161], v[28:31], v[72:75]
	ds_read_b128 v[158:161], v157 offset:128
	s_waitcnt lgkmcnt(0)
	v_mfma_f32_16x16x32_bf16 v[72:75], v[158:161], v[32:35], v[72:75]
	ds_read_b128 v[158:161], v157 offset:192
	v_mov_b32_e32 v157, 0xf149f2ca
	s_waitcnt lgkmcnt(0)
	v_mfma_f32_16x16x32_bf16 v[72:75], v[158:161], v[36:39], v[72:75]
	v_mov_b32_e32 v158, 0xf149f2ca
	ds_read_b32 v201, v216 offset:1364
	ds_read_b32 v203, v217 offset:1364
	ds_read_b32 v213, v218 offset:1364
	ds_read_b32 v215, v219 offset:1364
	s_nop 4
	v_mov_b32_e32 v200, v72
	v_mov_b32_e32 v202, v73
	v_mov_b32_e32 v212, v74
	v_mov_b32_e32 v214, v75
	s_waitcnt lgkmcnt(0)
	v_pk_mul_f32 v[200:201], v[200:201], s[62:63]
	v_pk_mul_f32 v[202:203], v[202:203], s[62:63]
	v_pk_mul_f32 v[212:213], v[212:213], s[62:63]
	v_pk_mul_f32 v[214:215], v[214:215], s[62:63]
	v_add_f32_e32 v200, v200, v201
	v_add_f32_e32 v202, v202, v203
	v_add_f32_e32 v212, v212, v213
	v_add_f32_e32 v214, v214, v215
	v_cndmask_b32_e64 v158, v204, v200, s[64:65]
	v_cndmask_b32_e64 v157, v204, v202, s[66:67]
	v_cndmask_b32_e64 v160, v204, v212, s[68:69]
	v_cndmask_b32_e64 v159, v204, v214, s[70:71]
	v_add_u32_e32 v72, s38, v128
	v_mad_i32_i24 v161, v72, s90, v118
	ds_read_b128 v[72:75], v161
	ds_read_b128 v[162:165], v161 offset:64
	s_waitcnt lgkmcnt(1)
; #define LAS __attribute__((address_space(3)))
; template <int L>
; __device__ __forceinline__ void layer_body(const Args& args, LAS unsigned char* lds, const int wave, const int G, const int gw, const int NGW, const int lo, const int hi,
;                                            unsigned char* const ws_kernel, const XcdBarrier& bar, int& pid) {
;     ...
;                     f32x4 sc[16];
; #pragma unroll
;                     for (int t = 0; t < 16; ++t) {
;                         const int irow = (r0w - krlo + (t >> 1)) * 40 + coloff + 16 * (t & 1);
;                         const unsigned ka = IMG + (unsigned)((irow + qi) * KPITCH + 16 * kg);
;                         f32x4 a = (f32x4){0.f, 0.f, 0.f, 0.f};
; #pragma unroll
;                         for (int ks = 0; ks < 4; ++ks) a = __builtin_amdgcn_mfma_f32_16x16x32_bf16(*(const LAS bf16x8*)(size_t)(ka + 64 * ks), qfn[ks], a, 0, 0, 0);
;                         const int dr = r0w + (t >> 1) - r + 7;
; #pragma unroll
;                         for (int j = 0; j < 4; ++j) { const int kc = cs + 16 * (t & 1) + 4 * kg + j; const bool valid = (kc >= wsq) && (kc < wsq + 16); const int dc = min(max(kc - c + 15, 0), 30);
;                             sc[t][j] = valid ? a[j] * scale_log2 + rl[dr * 31 + dc] * LOG2E : -1e30f; }
	v_mfma_f32_16x16x32_bf16 v[72:75], v[72:75], v[24:27], 0
	s_waitcnt lgkmcnt(0)
	v_mfma_f32_16x16x32_bf16 v[72:75], v[162:165], v[28:31], v[72:75]
	ds_read_b128 v[162:165], v161 offset:128
	s_waitcnt lgkmcnt(0)
	v_mfma_f32_16x16x32_bf16 v[72:75], v[162:165], v[32:35], v[72:75]
	ds_read_b128 v[162:165], v161 offset:192
	v_mov_b32_e32 v161, 0xf149f2ca
	s_waitcnt lgkmcnt(0)
	v_mfma_f32_16x16x32_bf16 v[72:75], v[162:165], v[36:39], v[72:75]
	v_mov_b32_e32 v162, 0xf149f2ca
	ds_read_b32 v201, v220 offset:1364
	ds_read_b32 v203, v221 offset:1364
	ds_read_b32 v213, v222 offset:1364
	ds_read_b32 v215, v223 offset:1364
	s_nop 4
	v_mov_b32_e32 v200, v72
	v_mov_b32_e32 v202, v73
	v_mov_b32_e32 v212, v74
	v_mov_b32_e32 v214, v75
	s_waitcnt lgkmcnt(0)
	v_pk_mul_f32 v[200:201], v[200:201], s[62:63]
	v_pk_mul_f32 v[202:203], v[202:203], s[62:63]
	v_pk_mul_f32 v[212:213], v[212:213], s[62:63]
	v_pk_mul_f32 v[214:215], v[214:215], s[62:63]
	v_add_f32_e32 v200, v200, v201
	v_add_f32_e32 v202, v202, v203
	v_add_f32_e32 v212, v212, v213
	v_add_f32_e32 v214, v214, v215
	v_cndmask_b32_e64 v162, v204, v200, s[72:73]
	v_cndmask_b32_e64 v161, v204, v202, s[74:75]
	v_cndmask_b32_e64 v164, v204, v212, s[76:77]
	v_cndmask_b32_e64 v163, v204, v214, s[0:1]
	s_add_i32 s39, s41, 0x168
	v_add_u32_e32 v72, s39, v121
	v_mad_i32_i24 v165, v72, s90, v118
	ds_read_b128 v[72:75], v165
	ds_read_b128 v[166:169], v165 offset:64
	s_waitcnt lgkmcnt(1)
	v_mfma_f32_16x16x32_bf16 v[72:75], v[72:75], v[24:27], 0
	s_waitcnt lgkmcnt(0)
	v_mfma_f32_16x16x32_bf16 v[72:75], v[166:169], v[28:31], v[72:75]
	ds_read_b128 v[166:169], v165 offset:128
	s_waitcnt lgkmcnt(0)
	v_mfma_f32_16x16x32_bf16 v[72:75], v[166:169], v[32:35], v[72:75]
	ds_read_b128 v[166:169], v165 offset:192
	v_mov_b32_e32 v165, 0xf149f2ca
	s_waitcnt lgkmcnt(0)
	v_mfma_f32_16x16x32_bf16 v[72:75], v[166:169], v[36:39], v[72:75]
	v_mov_b32_e32 v166, 0xf149f2ca
	ds_read_b32 v201, v216 offset:1488
	ds_read_b32 v203, v217 offset:1488
	ds_read_b32 v213, v218 offset:1488
	ds_read_b32 v215, v219 offset:1488
	s_nop 4
	v_mov_b32_e32 v200, v72
	v_mov_b32_e32 v202, v73
	v_mov_b32_e32 v212, v74
	v_mov_b32_e32 v214, v75
	s_waitcnt lgkmcnt(0)
	v_pk_mul_f32 v[200:201], v[200:201], s[62:63]
	v_pk_mul_f32 v[202:203], v[202:203], s[62:63]
	v_pk_mul_f32 v[212:213], v[212:213], s[62:63]
	v_pk_mul_f32 v[214:215], v[214:215], s[62:63]
	v_add_f32_e32 v200, v200, v201
	v_add_f32_e32 v202, v202, v203
	v_add_f32_e32 v212, v212, v213
	v_add_f32_e32 v214, v214, v215
	v_cndmask_b32_e64 v166, v204, v200, s[64:65]
	v_cndmask_b32_e64 v165, v204, v202, s[66:67]
	v_cndmask_b32_e64 v168, v204, v212, s[68:69]
	v_cndmask_b32_e64 v167, v204, v214, s[70:71]
	v_add_u32_e32 v72, s39, v128
	v_mad_i32_i24 v169, v72, s90, v118
	ds_read_b128 v[72:75], v169
	ds_read_b128 v[170:173], v169 offset:64
	s_waitcnt lgkmcnt(1)
	v_mfma_f32_16x16x32_bf16 v[72:75], v[72:75], v[24:27], 0
	s_waitcnt lgkmcnt(0)
	v_mfma_f32_16x16x32_bf16 v[72:75], v[170:173], v[28:31], v[72:75]
	ds_read_b128 v[170:173], v169 offset:128
	s_waitcnt lgkmcnt(0)
	v_mfma_f32_16x16x32_bf16 v[72:75], v[170:173], v[32:35], v[72:75]
	ds_read_b128 v[170:173], v169 offset:192
	v_mov_b32_e32 v169, 0xf149f2ca
	s_waitcnt lgkmcnt(0)
	v_mfma_f32_16x16x32_bf16 v[72:75], v[170:173], v[36:39], v[72:75]
	v_mov_b32_e32 v170, 0xf149f2ca
	ds_read_b32 v201, v220 offset:1488
	ds_read_b32 v203, v221 offset:1488
	ds_read_b32 v213, v222 offset:1488
	ds_read_b32 v215, v223 offset:1488
	s_nop 4
	v_mov_b32_e32 v200, v72
	v_mov_b32_e32 v202, v73
	v_mov_b32_e32 v212, v74
	v_mov_b32_e32 v214, v75
	s_waitcnt lgkmcnt(0)
	v_pk_mul_f32 v[200:201], v[200:201], s[62:63]
	v_pk_mul_f32 v[202:203], v[202:203], s[62:63]
	v_pk_mul_f32 v[212:213], v[212:213], s[62:63]
	v_pk_mul_f32 v[214:215], v[214:215], s[62:63]
	v_add_f32_e32 v200, v200, v201
	v_add_f32_e32 v202, v202, v203
	v_add_f32_e32 v212, v212, v213
	v_add_f32_e32 v214, v214, v215
	v_cndmask_b32_e64 v170, v204, v200, s[72:73]
	v_cndmask_b32_e64 v169, v204, v202, s[74:75]
	v_cndmask_b32_e64 v172, v204, v212, s[76:77]
	v_cndmask_b32_e64 v171, v204, v214, s[0:1]
	s_add_i32 s40, s41, 0x190
	v_add_u32_e32 v72, s40, v121
	v_mad_i32_i24 v173, v72, s90, v118
	ds_read_b128 v[72:75], v173
	ds_read_b128 v[174:177], v173 offset:64
	s_waitcnt lgkmcnt(1)
	v_mfma_f32_16x16x32_bf16 v[72:75], v[72:75], v[24:27], 0
	s_waitcnt lgkmcnt(0)
	v_mfma_f32_16x16x32_bf16 v[72:75], v[174:177], v[28:31], v[72:75]
	ds_read_b128 v[174:177], v173 offset:128
	s_waitcnt lgkmcnt(0)
	v_mfma_f32_16x16x32_bf16 v[72:75], v[174:177], v[32:35], v[72:75]
	ds_read_b128 v[174:177], v173 offset:192
	v_mov_b32_e32 v173, 0xf149f2ca
	s_waitcnt lgkmcnt(0)
	v_mfma_f32_16x16x32_bf16 v[72:75], v[174:177], v[36:39], v[72:75]
	v_mov_b32_e32 v174, 0xf149f2ca
	ds_read_b32 v201, v216 offset:1612
	ds_read_b32 v203, v217 offset:1612
	ds_read_b32 v213, v218 offset:1612
	ds_read_b32 v215, v219 offset:1612
	s_nop 4
	v_mov_b32_e32 v200, v72
	v_mov_b32_e32 v202, v73
	v_mov_b32_e32 v212, v74
	v_mov_b32_e32 v214, v75
	s_waitcnt lgkmcnt(0)
	v_pk_mul_f32 v[200:201], v[200:201], s[62:63]
	v_pk_mul_f32 v[202:203], v[202:203], s[62:63]
	v_pk_mul_f32 v[212:213], v[212:213], s[62:63]
	v_pk_mul_f32 v[214:215], v[214:215], s[62:63]
	v_add_f32_e32 v200, v200, v201
	v_add_f32_e32 v202, v202, v203
	v_add_f32_e32 v212, v212, v213
	v_add_f32_e32 v214, v214, v215
	v_cndmask_b32_e64 v174, v204, v200, s[64:65]
	v_cndmask_b32_e64 v173, v204, v202, s[66:67]
	v_cndmask_b32_e64 v176, v204, v212, s[68:69]
	v_cndmask_b32_e64 v175, v204, v214, s[70:71]
	v_add_u32_e32 v72, s40, v128
	v_mad_i32_i24 v177, v72, s90, v118
	ds_read_b128 v[72:75], v177
	ds_read_b128 v[178:181], v177 offset:64
	s_waitcnt lgkmcnt(1)
; #define LAS __attribute__((address_space(3)))
; template <int L>
; __device__ __forceinline__ void layer_body(const Args& args, LAS unsigned char* lds, const int wave, const int G, const int gw, const int NGW, const int lo, const int hi,
;                                            unsigned char* const ws_kernel, const XcdBarrier& bar, int& pid) {
;     ...
;                     f32x4 sc[16];
; #pragma unroll
;                     for (int t = 0; t < 16; ++t) {
;                         const int irow = (r0w - krlo + (t >> 1)) * 40 + coloff + 16 * (t & 1);
;                         const unsigned ka = IMG + (unsigned)((irow + qi) * KPITCH + 16 * kg);
;                         f32x4 a = (f32x4){0.f, 0.f, 0.f, 0.f};
; #pragma unroll
;                         for (int ks = 0; ks < 4; ++ks) a = __builtin_amdgcn_mfma_f32_16x16x32_bf16(*(const LAS bf16x8*)(size_t)(ka + 64 * ks), qfn[ks], a, 0, 0, 0);
;                         const int dr = r0w + (t >> 1) - r + 7;
; #pragma unroll
;                         for (int j = 0; j < 4; ++j) { const int kc = cs + 16 * (t & 1) + 4 * kg + j; const bool valid = (kc >= wsq) && (kc < wsq + 16); const int dc = min(max(kc - c + 15, 0), 30);
;                             sc[t][j] = valid ? a[j] * scale_log2 + rl[dr * 31 + dc] * LOG2E : -1e30f; }
;                         __builtin_amdgcn_sched_barrier(0);
;                     }
;                     float mx = -1e30f;
; #pragma unroll
;                     for (int t = 0; t < 16; ++t)
; #pragma unroll
;                         for (int j = 0; j < 4; ++j) mx = fmaxf(mx, sc[t][j]);
;                     mx = fmaxf(mx, __shfl_xor(mx, 16)); mx = fmaxf(mx, __shfl_xor(mx, 32));
	v_mfma_f32_16x16x32_bf16 v[72:75], v[72:75], v[24:27], 0
	s_waitcnt lgkmcnt(0)
	v_mfma_f32_16x16x32_bf16 v[72:75], v[178:181], v[28:31], v[72:75]
	ds_read_b128 v[178:181], v177 offset:128
	s_waitcnt lgkmcnt(0)
	v_mfma_f32_16x16x32_bf16 v[72:75], v[178:181], v[32:35], v[72:75]
	ds_read_b128 v[178:181], v177 offset:192
	v_mov_b32_e32 v177, 0xf149f2ca
	s_waitcnt lgkmcnt(0)
	v_mfma_f32_16x16x32_bf16 v[72:75], v[178:181], v[36:39], v[72:75]
	v_mov_b32_e32 v178, 0xf149f2ca
	ds_read_b32 v201, v220 offset:1612
	ds_read_b32 v203, v221 offset:1612
	ds_read_b32 v213, v222 offset:1612
	ds_read_b32 v215, v223 offset:1612
	s_nop 4
	v_mov_b32_e32 v200, v72
	v_mov_b32_e32 v202, v73
	v_mov_b32_e32 v212, v74
	v_mov_b32_e32 v214, v75
	s_waitcnt lgkmcnt(0)
	v_pk_mul_f32 v[200:201], v[200:201], s[62:63]
	v_pk_mul_f32 v[202:203], v[202:203], s[62:63]
	v_pk_mul_f32 v[212:213], v[212:213], s[62:63]
	v_pk_mul_f32 v[214:215], v[214:215], s[62:63]
	v_add_f32_e32 v200, v200, v201
	v_add_f32_e32 v202, v202, v203
	v_add_f32_e32 v212, v212, v213
	v_add_f32_e32 v214, v214, v215
	v_cndmask_b32_e64 v178, v204, v200, s[72:73]
	v_cndmask_b32_e64 v177, v204, v202, s[74:75]
	v_cndmask_b32_e64 v191, v204, v212, s[76:77]
	v_cndmask_b32_e64 v188, v204, v214, s[0:1]
	s_addk_i32 s41, 0x1b8
	v_add_u32_e32 v72, s41, v121
	v_mad_i32_i24 v121, v72, s90, v118
	ds_read_b128 v[72:75], v121
	ds_read_b128 v[180:183], v121 offset:64
	v_mov_b32_e32 v205, 0xf149f2ca
	s_waitcnt lgkmcnt(1)
	v_mfma_f32_16x16x32_bf16 v[72:75], v[72:75], v[24:27], 0
	s_waitcnt lgkmcnt(0)
	v_mfma_f32_16x16x32_bf16 v[72:75], v[180:183], v[28:31], v[72:75]
	ds_read_b128 v[180:183], v121 offset:128
	s_waitcnt lgkmcnt(0)
	v_mfma_f32_16x16x32_bf16 v[72:75], v[180:183], v[32:35], v[72:75]
	ds_read_b128 v[180:183], v121 offset:192
	v_mov_b32_e32 v121, 0xf149f2ca
	s_waitcnt lgkmcnt(0)
	v_mfma_f32_16x16x32_bf16 v[72:75], v[180:183], v[36:39], v[72:75]
	ds_read_b32 v201, v216 offset:1736
	ds_read_b32 v203, v217 offset:1736
	ds_read_b32 v213, v218 offset:1736
	ds_read_b32 v215, v219 offset:1736
	s_nop 4
	v_mov_b32_e32 v200, v72
	v_mov_b32_e32 v202, v73
	v_mov_b32_e32 v212, v74
	v_mov_b32_e32 v214, v75
	s_waitcnt lgkmcnt(0)
	v_pk_mul_f32 v[200:201], v[200:201], s[62:63]
	v_pk_mul_f32 v[202:203], v[202:203], s[62:63]
	v_pk_mul_f32 v[212:213], v[212:213], s[62:63]
	v_pk_mul_f32 v[214:215], v[214:215], s[62:63]
	v_add_f32_e32 v200, v200, v201
	v_add_f32_e32 v202, v202, v203
	v_add_f32_e32 v212, v212, v213
	v_add_f32_e32 v214, v214, v215
	v_cndmask_b32_e64 v205, v204, v200, s[64:65]
	v_cndmask_b32_e64 v121, v204, v202, s[66:67]
	v_cndmask_b32_e64 v207, v204, v212, s[68:69]
	v_cndmask_b32_e64 v206, v204, v214, s[70:71]
	v_add_u32_e32 v72, s41, v128
	v_mad_i32_i24 v118, v72, s90, v118
	ds_read_b128 v[72:75], v118
	ds_read_b128 v[124:127], v118 offset:64
	v_mov_b32_e32 v208, 0xf149f2ca
	v_mov_b32_e32 v209, 0xf149f2ca
	s_waitcnt lgkmcnt(1)
	v_mfma_f32_16x16x32_bf16 v[72:75], v[72:75], v[24:27], 0
	s_waitcnt lgkmcnt(0)
	v_mfma_f32_16x16x32_bf16 v[72:75], v[124:127], v[28:31], v[72:75]
	ds_read_b128 v[124:127], v118 offset:128
	s_waitcnt lgkmcnt(0)
	v_mfma_f32_16x16x32_bf16 v[72:75], v[124:127], v[32:35], v[72:75]
	ds_read_b128 v[124:127], v118 offset:192
	s_waitcnt lgkmcnt(0)
	v_mfma_f32_16x16x32_bf16 v[72:75], v[124:127], v[36:39], v[72:75]
	ds_read_b32 v201, v220 offset:1736
	ds_read_b32 v203, v221 offset:1736
	ds_read_b32 v213, v222 offset:1736
	ds_read_b32 v215, v223 offset:1736
	s_nop 4
	v_mov_b32_e32 v200, v72
	v_mov_b32_e32 v202, v73
	v_mov_b32_e32 v212, v74
	v_mov_b32_e32 v214, v75
	s_waitcnt lgkmcnt(0)
	v_pk_mul_f32 v[200:201], v[200:201], s[62:63]
	v_pk_mul_f32 v[202:203], v[202:203], s[62:63]
	v_pk_mul_f32 v[212:213], v[212:213], s[62:63]
	v_pk_mul_f32 v[214:215], v[214:215], s[62:63]
	v_add_f32_e32 v200, v200, v201
	v_add_f32_e32 v202, v202, v203
	v_add_f32_e32 v212, v212, v213
	v_add_f32_e32 v214, v214, v215
	v_cndmask_b32_e64 v209, v204, v200, s[72:73]
	v_cndmask_b32_e64 v208, v204, v202, s[74:75]
	v_cndmask_b32_e64 v211, v204, v212, s[76:77]
	v_cndmask_b32_e64 v210, v204, v214, s[0:1]
	s_lshl_b32 s36, s36, 7
	s_mov_b32 s0, 0xf149f2ca
	v_max3_f32 v72, v115, s0, v104
	v_max3_f32 v72, v72, v117, v116
	v_max3_f32 v72, v72, v120, v119
	v_max3_f32 v72, v72, v123, v122
	v_max3_f32 v72, v72, v131, v129
	v_max3_f32 v72, v72, v136, v135
	v_max3_f32 v72, v72, v138, v137
	v_max3_f32 v72, v72, v140, v139
	v_max3_f32 v72, v72, v142, v141
	v_max3_f32 v72, v72, v144, v143
	v_max3_f32 v72, v72, v146, v145
	v_max3_f32 v72, v72, v148, v147
	v_max3_f32 v72, v72, v150, v149
	v_max3_f32 v72, v72, v152, v151
	v_max3_f32 v72, v72, v154, v153
	v_max3_f32 v72, v72, v156, v155
	v_max3_f32 v72, v72, v158, v157
	v_max3_f32 v72, v72, v160, v159
	v_max3_f32 v72, v72, v162, v161
	v_max3_f32 v72, v72, v164, v163
	v_max3_f32 v72, v72, v166, v165
	v_max3_f32 v72, v72, v168, v167
	v_max3_f32 v72, v72, v170, v169
	v_max3_f32 v72, v72, v172, v171
	v_max3_f32 v72, v72, v174, v173
	v_max3_f32 v72, v72, v176, v175
	v_max3_f32 v72, v72, v178, v177
	v_max3_f32 v72, v72, v191, v188
	v_and_b32_e32 v74, 64, v107
	v_max3_f32 v72, v72, v205, v121
	v_xor_b32_e32 v73, 16, v107
	v_add_u32_e32 v74, 64, v74
	v_max3_f32 v72, v72, v207, v206
	v_cmp_lt_i32_e32 vcc, v73, v74
	v_max3_f32 v72, v72, v209, v208
	v_max3_f32 v72, v72, v211, v210
	v_cndmask_b32_e32 v73, v107, v73, vcc
	v_lshlrev_b32_e32 v212, 2, v73
	ds_bpermute_b32 v73, v212, v72
	s_waitcnt lgkmcnt(0)
	s_barrier
; template <int L>
; __device__ __forceinline__ void layer_body(const Args& args, LAS unsigned char* lds, const int wave, const int G, const int gw, const int NGW, const int lo, const int hi,
;                                            unsigned char* const ws_kernel, const XcdBarrier& bar, int& pid) {
;     ...
;                     mx = fmaxf(mx, __shfl_xor(mx, 16)); mx = fmaxf(mx, __shfl_xor(mx, 32));
;                     float sum = 0.f;
; #pragma unroll
;                     for (int t = 0; t < 16; ++t)
; #pragma unroll
;                         for (int j = 0; j < 4; ++j) { sc[t][j] = __builtin_amdgcn_exp2f(sc[t][j] - mx); sum += sc[t][j]; }
;                     sum += __shfl_xor(sum, 16); sum += __shfl_xor(sum, 32);
	s_add_i32 s21, s21, s86
	v_max_f32_e32 v73, v73, v73
	v_max_f32_e32 v72, v72, v73
	v_xor_b32_e32 v73, 32, v107
	v_cmp_lt_i32_e32 vcc, v73, v74
	s_cmp_ge_i32 s21, s52
	s_cselect_b64 s[0:1], -1, 0
	v_cndmask_b32_e32 v73, v107, v73, vcc
	v_lshlrev_b32_e32 v213, 2, v73
	ds_bpermute_b32 v73, v213, v72
	s_and_b64 vcc, exec, s[0:1]
	s_waitcnt lgkmcnt(0)
	v_max_f32_e32 v73, v73, v73
	v_max_f32_e32 v214, v72, v73
	v_sub_f32_e32 v72, v115, v214
	v_exp_f32_e32 v192, v72
	v_sub_f32_e32 v72, v104, v214
	v_exp_f32_e32 v200, v72
	v_sub_f32_e32 v72, v117, v214
	v_exp_f32_e32 v196, v72
	v_sub_f32_e32 v72, v116, v214
	v_exp_f32_e32 v202, v72
	v_sub_f32_e32 v72, v120, v214
	v_sub_f32_e32 v104, v208, v214
	v_exp_f32_e32 v198, v72
	v_sub_f32_e32 v72, v119, v214
	v_exp_f32_e32 v119, v104
	v_sub_f32_e32 v104, v211, v214
	v_exp_f32_e32 v116, v104
	v_sub_f32_e32 v104, v210, v214
	v_sub_f32_e32 v73, v121, v214
	v_exp_f32_e32 v121, v104
	v_add_f32_e32 v104, 0, v192
	v_exp_f32_e32 v203, v72
	v_sub_f32_e32 v72, v123, v214
	v_add_f32_e32 v104, v200, v104
	v_exp_f32_e32 v201, v72
	v_sub_f32_e32 v72, v122, v214
	v_add_f32_e32 v104, v196, v104
	v_exp_f32_e32 v204, v72
	v_sub_f32_e32 v72, v131, v214
	v_add_f32_e32 v104, v202, v104
	v_exp_f32_e32 v182, v72
	v_sub_f32_e32 v72, v129, v214
	v_add_f32_e32 v104, v198, v104
	v_exp_f32_e32 v193, v72
	v_sub_f32_e32 v72, v136, v214
	v_add_f32_e32 v104, v203, v104
	v_exp_f32_e32 v186, v72
	v_sub_f32_e32 v72, v135, v214
	v_add_f32_e32 v104, v201, v104
	v_exp_f32_e32 v195, v72
	v_sub_f32_e32 v72, v138, v214
	v_add_f32_e32 v104, v204, v104
	v_exp_f32_e32 v189, v72
	v_sub_f32_e32 v72, v137, v214
	v_add_f32_e32 v104, v182, v104
	v_exp_f32_e32 v197, v72
	v_sub_f32_e32 v72, v140, v214
	v_add_f32_e32 v104, v193, v104
	v_exp_f32_e32 v194, v72
	v_sub_f32_e32 v72, v139, v214
	v_add_f32_e32 v104, v186, v104
	v_exp_f32_e32 v199, v72
	v_sub_f32_e32 v72, v142, v214
	v_add_f32_e32 v104, v195, v104
	v_exp_f32_e32 v179, v72
	v_sub_f32_e32 v72, v141, v214
	v_add_f32_e32 v104, v189, v104
	v_exp_f32_e32 v183, v72
	v_sub_f32_e32 v72, v144, v214
	v_add_f32_e32 v104, v197, v104
	v_exp_f32_e32 v180, v72
	v_sub_f32_e32 v72, v143, v214
	v_add_f32_e32 v104, v194, v104
	v_exp_f32_e32 v185, v72
	v_sub_f32_e32 v72, v146, v214
	v_add_f32_e32 v104, v199, v104
	v_exp_f32_e32 v181, v72
	v_sub_f32_e32 v72, v145, v214
	v_add_f32_e32 v104, v179, v104
	v_exp_f32_e32 v187, v72
	v_sub_f32_e32 v72, v148, v214
	v_add_f32_e32 v104, v183, v104
	v_exp_f32_e32 v184, v72
	v_sub_f32_e32 v72, v147, v214
	v_add_f32_e32 v104, v180, v104
	v_exp_f32_e32 v190, v72
	v_sub_f32_e32 v72, v150, v214
	v_add_f32_e32 v104, v185, v104
	v_exp_f32_e32 v138, v72
	v_sub_f32_e32 v72, v149, v214
	v_add_f32_e32 v104, v181, v104
	v_exp_f32_e32 v146, v72
	v_sub_f32_e32 v72, v152, v214
	v_add_f32_e32 v104, v187, v104
	v_exp_f32_e32 v142, v72
	v_sub_f32_e32 v72, v151, v214
	v_add_f32_e32 v104, v184, v104
	v_exp_f32_e32 v148, v72
	v_sub_f32_e32 v72, v154, v214
	v_add_f32_e32 v104, v190, v104
	v_exp_f32_e32 v144, v72
	v_sub_f32_e32 v72, v153, v214
	v_add_f32_e32 v104, v138, v104
	v_exp_f32_e32 v150, v72
	v_sub_f32_e32 v72, v156, v214
	v_add_f32_e32 v104, v146, v104
	v_exp_f32_e32 v147, v72
	v_sub_f32_e32 v72, v155, v214
	v_add_f32_e32 v104, v142, v104
	v_exp_f32_e32 v152, v72
	v_sub_f32_e32 v72, v158, v214
	v_add_f32_e32 v104, v148, v104
	v_exp_f32_e32 v130, v72
	v_sub_f32_e32 v72, v157, v214
	v_add_f32_e32 v104, v144, v104
	v_exp_f32_e32 v139, v72
	v_sub_f32_e32 v72, v160, v214
	v_add_f32_e32 v104, v150, v104
	v_exp_f32_e32 v134, v72
	v_sub_f32_e32 v72, v159, v214
	v_add_f32_e32 v104, v147, v104
	v_exp_f32_e32 v141, v72
	v_sub_f32_e32 v72, v162, v214
	v_add_f32_e32 v104, v152, v104
	v_exp_f32_e32 v136, v72
	v_sub_f32_e32 v72, v161, v214
	v_add_f32_e32 v104, v130, v104
	v_exp_f32_e32 v143, v72
	v_sub_f32_e32 v72, v164, v214
	v_add_f32_e32 v104, v139, v104
	v_exp_f32_e32 v140, v72
	v_sub_f32_e32 v72, v163, v214
	v_add_f32_e32 v104, v134, v104
	v_exp_f32_e32 v145, v72
	v_sub_f32_e32 v72, v166, v214
	v_add_f32_e32 v104, v141, v104
	v_exp_f32_e32 v122, v72
	v_sub_f32_e32 v72, v165, v214
	v_add_f32_e32 v104, v136, v104
	v_exp_f32_e32 v131, v72
	v_sub_f32_e32 v72, v168, v214
	v_add_f32_e32 v104, v143, v104
	v_exp_f32_e32 v126, v72
	v_sub_f32_e32 v72, v167, v214
	v_add_f32_e32 v104, v140, v104
	v_exp_f32_e32 v133, v72
	v_sub_f32_e32 v72, v170, v214
	v_add_f32_e32 v104, v145, v104
	v_exp_f32_e32 v128, v72
	v_sub_f32_e32 v72, v169, v214
	v_add_f32_e32 v104, v122, v104
	v_exp_f32_e32 v135, v72
	v_sub_f32_e32 v72, v172, v214
	v_add_f32_e32 v104, v131, v104
	v_exp_f32_e32 v132, v72
	v_sub_f32_e32 v72, v171, v214
	v_add_f32_e32 v104, v126, v104
	v_exp_f32_e32 v137, v72
	v_sub_f32_e32 v72, v174, v214
	v_add_f32_e32 v104, v133, v104
	v_exp_f32_e32 v75, v72
	v_sub_f32_e32 v72, v173, v214
	v_add_f32_e32 v104, v128, v104
	v_exp_f32_e32 v123, v72
	v_sub_f32_e32 v72, v176, v214
	v_add_f32_e32 v104, v135, v104
	v_exp_f32_e32 v118, v72
	v_sub_f32_e32 v72, v175, v214
	v_add_f32_e32 v104, v132, v104
	v_exp_f32_e32 v125, v72
	v_sub_f32_e32 v72, v178, v214
	v_add_f32_e32 v104, v137, v104
	v_exp_f32_e32 v120, v72
	v_sub_f32_e32 v72, v177, v214
	v_add_f32_e32 v104, v75, v104
	v_exp_f32_e32 v127, v72
	v_sub_f32_e32 v72, v191, v214
	v_add_f32_e32 v104, v123, v104
	v_exp_f32_e32 v124, v72
	v_sub_f32_e32 v72, v188, v214
	v_add_f32_e32 v104, v118, v104
	v_exp_f32_e32 v129, v72
	v_sub_f32_e32 v72, v205, v214
	v_add_f32_e32 v104, v125, v104
	v_exp_f32_e32 v72, v72
	v_add_f32_e32 v104, v120, v104
	v_exp_f32_e32 v115, v73
	v_sub_f32_e32 v73, v207, v214
	v_add_f32_e32 v104, v127, v104
	v_exp_f32_e32 v73, v73
	v_sub_f32_e32 v74, v206, v214
	v_add_f32_e32 v104, v124, v104
	v_exp_f32_e32 v117, v74
	v_sub_f32_e32 v74, v209, v214
	v_add_f32_e32 v104, v129, v104
	v_exp_f32_e32 v74, v74
	v_add_f32_e32 v104, v72, v104
	v_add_f32_e32 v104, v115, v104
	v_add_f32_e32 v104, v73, v104
	v_add_f32_e32 v104, v117, v104
	v_add_f32_e32 v104, v74, v104
	v_add_f32_e32 v104, v119, v104
	v_add_f32_e32 v104, v116, v104
	v_add_f32_e32 v104, v121, v104
	ds_bpermute_b32 v149, v212, v104
	v_lshlrev_b32_e32 v153, 2, v77
	v_and_b32_e32 v153, 12, v153
	s_waitcnt lgkmcnt(0)
; #define LAS __attribute__((address_space(3)))
; __device__ __forceinline__ unsigned pk2(float lo, float hi) { return f2bf(lo) | (f2bf(hi) << 16); }
; template <int L>
; __device__ __forceinline__ void layer_body(const Args& args, LAS unsigned char* lds, const int wave, const int G, const int gw, const int NGW, const int lo, const int hi,
;                                            unsigned char* const ws_kernel, const XcdBarrier& bar, int& pid) {
;     ...
;                     sum += __shfl_xor(sum, 16); sum += __shfl_xor(sum, 32);
;                     bf16x8 pbf[8];
; #pragma unroll
;                     for (int s = 0; s < 8; ++s) { const f32x4 p0 = sc[2 * s], p1 = sc[2 * s + 1]; v4u w; w.x = pk2(p0[0], p0[1]); w.y = pk2(p0[2], p0[3]); w.z = pk2(p1[0], p1[1]); w.w = pk2(p1[2], p1[3]); pbf[s] = __builtin_bit_cast(bf16x8, w); }
;                     __syncthreads();
; #pragma unroll
;                     for (int i = 0; i < 14; ++i) { const int kid = skey + 32 * i; *(LAS v4u*)(size_t)(IMG + vimg_off(kid, sch)) = rst[i]; }
;                     __syncthreads();
;                     if (unit + GH < UEND) { NA_LOADROWS(unit + GH, rst, D); NA_LOADQ(unit + GH); }
	v_add_f32_e32 v149, v104, v149
	v_lshlrev_b32_e32 v104, 8, v77
	v_bfe_u32 v77, v77, 2, 2
	v_bitop3_b32 v77, v153, v112, v77 bitop3:0x36
	v_lshlrev_b32_e32 v77, 4, v77
	v_add3_u32 v77, v104, 0, v77
	ds_bpermute_b32 v151, v213, v149
	v_add_u32_e32 v104, 0x10000, v77
	s_waitcnt vmcnt(13)
	ds_write_b128 v77, v[0:3]
	s_waitcnt vmcnt(12)
	ds_write_b128 v77, v[4:7] offset:8192
	s_waitcnt vmcnt(11)
	ds_write_b128 v77, v[8:11] offset:16384
	s_waitcnt vmcnt(10)
	ds_write_b128 v77, v[12:15] offset:24576
	s_waitcnt vmcnt(9)
	ds_write_b128 v77, v[16:19] offset:32768
	s_waitcnt vmcnt(8)
	ds_write_b128 v77, v[20:23] offset:40960
	s_waitcnt vmcnt(7)
	ds_write_b128 v77, v[40:43] offset:49152
	s_waitcnt vmcnt(6)
	ds_write_b128 v77, v[44:47] offset:57344
	s_waitcnt vmcnt(5)
	ds_write_b128 v104, v[48:51]
	v_add_u32_e32 v104, 0x12000, v77
	s_waitcnt vmcnt(4)
	ds_write_b128 v104, v[52:55]
	v_add_u32_e32 v104, 0x14000, v77
	s_waitcnt vmcnt(3)
	ds_write_b128 v104, v[56:59]
	v_add_u32_e32 v104, 0x16000, v77
	s_waitcnt vmcnt(2)
	ds_write_b128 v104, v[60:63]
	v_add_u32_e32 v104, 0x18000, v77
	v_add_u32_e32 v77, 0x1a000, v77
	s_waitcnt vmcnt(1)
	ds_write_b128 v104, v[64:67]
	s_waitcnt vmcnt(0)
	ds_write_b128 v77, v[68:71]
	s_waitcnt lgkmcnt(0)
	s_barrier
	s_cbranch_vccnz .LBB0_843
	s_add_i32 s42, s83, s84
	s_and_b32 s45, s42, 28
	s_add_i32 s47, s91, s96
	v_sub_u32_e64 v1, s45, 1 clamp
	s_and_b32 s42, s47, 0x780
	v_lshlrev_b32_e32 v0, 3, v112
	s_and_b32 s44, s21, 1
	s_max_u32 s46, s45, 4
	v_min_u32_e32 v1, 24, v1
	s_lshl_b32 s48, s42, 1
	s_add_u32 s42, s59, s48
	v_lshlrev_b32_e32 v104, 1, v0
	v_subrev_u32_e32 v0, s46, v1
	s_addc_u32 s43, s80, 0
	v_add_u32_e32 v31, 11, v0
	v_sub_u32_e64 v30, s45, 4 clamp
	v_lshl_add_u64 v[24:25], s[42:43], 0, v[104:105]
	s_and_b32 s46, s47, 0xfffff800
	s_mul_i32 s42, s44, 24
	v_min_i32_e32 v0, v78, v31
	v_min_i32_e32 v2, v80, v31
	v_min_i32_e32 v8, v82, v31
	v_min_i32_e32 v10, v84, v31
	v_min_i32_e32 v16, v86, v31
	v_min_i32_e32 v18, v88, v31
	v_min_i32_e32 v26, v90, v31
	v_min_i32_e32 v28, v92, v31
	s_or_b32 s47, s46, s42
	v_add_lshl_u32 v0, v0, v30, 6
	v_add_lshl_u32 v2, v2, v30, 6
	v_add_lshl_u32 v8, v8, v30, 6
	v_add_lshl_u32 v10, v10, v30, 6
	v_add_lshl_u32 v16, v16, v30, 6
	v_add_lshl_u32 v18, v18, v30, 6
	v_add_lshl_u32 v26, v26, v30, 6
	v_add_lshl_u32 v28, v28, v30, 6
	v_add3_u32 v0, v79, s47, v0
	v_add3_u32 v2, v81, s47, v2
	v_add3_u32 v8, v83, s47, v8
	v_add3_u32 v10, v85, s47, v10
	v_add3_u32 v16, v87, s47, v16
	v_add3_u32 v18, v89, s47, v18
	v_add3_u32 v26, v91, s47, v26
	v_add3_u32 v28, v93, s47, v28
	v_mad_i64_i32 v[0:1], s[42:43], v0, s22, v[24:25]
	v_mad_i64_i32 v[4:5], s[42:43], v2, s22, v[24:25]
	v_mad_i64_i32 v[8:9], s[42:43], v8, s22, v[24:25]
	v_mad_i64_i32 v[12:13], s[42:43], v10, s22, v[24:25]
	v_mad_i64_i32 v[16:17], s[42:43], v16, s22, v[24:25]
	v_mad_i64_i32 v[20:21], s[42:43], v18, s22, v[24:25]
	v_mad_i64_i32 v[26:27], s[42:43], v26, s22, v[24:25]
	v_mad_i64_i32 v[28:29], s[42:43], v28, s22, v[24:25]
	global_load_dwordx4 v[0:3], v[0:1], off
	s_nop 0
	global_load_dwordx4 v[4:7], v[4:5], off
	s_nop 0
	global_load_dwordx4 v[8:11], v[8:9], off
	s_nop 0
	global_load_dwordx4 v[12:15], v[12:13], off
	s_nop 0
	global_load_dwordx4 v[16:19], v[16:17], off
	s_nop 0
	global_load_dwordx4 v[20:23], v[20:21], off
	s_nop 0
	global_load_dwordx4 v[40:43], v[26:27], off
	global_load_dwordx4 v[44:47], v[28:29], off
	v_min_i32_e32 v26, v94, v31
	v_min_i32_e32 v28, v96, v31
	v_add_lshl_u32 v26, v26, v30, 6
	v_add_lshl_u32 v28, v28, v30, 6
	v_add3_u32 v26, v95, s47, v26
	v_add3_u32 v28, v97, s47, v28
	v_mad_i64_i32 v[26:27], s[42:43], v26, s22, v[24:25]
	v_mad_i64_i32 v[28:29], s[42:43], v28, s22, v[24:25]
	global_load_dwordx4 v[48:51], v[26:27], off
	global_load_dwordx4 v[52:55], v[28:29], off
	v_min_i32_e32 v26, v98, v31
	v_min_i32_e32 v28, v100, v31
	v_add_lshl_u32 v26, v26, v30, 6
	v_add_lshl_u32 v28, v28, v30, 6
	v_add3_u32 v26, v99, s47, v26
	v_add3_u32 v28, v101, s47, v28
	v_mad_i64_i32 v[26:27], s[42:43], v26, s22, v[24:25]
	v_mad_i64_i32 v[28:29], s[42:43], v28, s22, v[24:25]
	global_load_dwordx4 v[56:59], v[26:27], off
	global_load_dwordx4 v[60:63], v[28:29], off
	v_min_i32_e32 v26, v102, v31
	v_min_i32_e32 v28, v113, v31
	v_add_lshl_u32 v26, v26, v30, 6
	v_add_lshl_u32 v28, v28, v30, 6
	v_add3_u32 v26, v103, s47, v26
	v_add3_u32 v28, v114, s47, v28
	v_mad_i64_i32 v[26:27], s[42:43], v26, s22, v[24:25]
	v_mad_i64_i32 v[24:25], s[42:43], v28, s22, v[24:25]
	s_add_u32 s42, s55, s48
	s_addc_u32 s43, s56, 0
	s_add_i32 s45, s45, s53
	s_lshl_b32 s45, s45, 6
	s_add_i32 s45, s45, s46
	s_lshl_b32 s44, s44, 5
	s_or_b32 s44, s45, s44
	s_or_b32 s44, s44, s54
	global_load_dwordx4 v[64:67], v[26:27], off
	global_load_dwordx4 v[68:71], v[24:25], off
	v_or_b32_e32 v26, s44, v112
	v_mov_b64_e32 v[24:25], s[42:43]
	v_mad_i64_i32 v[24:25], s[42:43], v26, s22, v[24:25]
	v_lshlrev_b32_e32 v104, 4, v76
	v_lshl_add_u64 v[36:37], v[24:25], 0, v[104:105]
	global_load_dwordx4 v[24:27], v[36:37], off
	global_load_dwordx4 v[28:31], v[36:37], off offset:64
	global_load_dwordx4 v[32:35], v[36:37], off offset:128
	s_nop 0
	global_load_dwordx4 v[36:39], v[36:37], off offset:192
	s_branch .LBB0_843

; #define LAS __attribute__((address_space(3)))
; #define NA_DECODE(u_, b, h, rbase, hc, krlo, nkr) do { hc = (u_) & 1; const int rg_ = ((u_) >> 1) & 7; h = ((u_) >> 4) & 15; b = (u_) >> 8; rbase = 4 * rg_; \
;                     krlo = min(max(rbase - 4, 0), 24); nkr = min(max(rbase - 1, 0), 24) + 8 - krlo; } while (0)
; template <int L>
; __device__ __forceinline__ void layer_body(const Args& args, LAS unsigned char* lds, const int wave, const int G, const int gw, const int NGW, const int lo, const int hi,
;                                            unsigned char* const ws_kernel, const XcdBarrier& bar, int& pid) {
;     ...
;                 int unit = vcu;
;                 { const int qi = lane & 15, kg = lane >> 4, sch = tid & 15, skey = tid >> 4; if (unit < UEND) { NA_LOADROWS(unit, rst, D); NA_LOADQ(unit); } }
;                 for (; unit < UEND; unit += GH) {
;                     int b, h, rbase, hc, krlo, nkr; NA_DECODE(unit, b, h, rbase, hc, krlo, nkr);
;                     int tl_ = tid; asm volatile("" : "+v"(tl_));
;                     const int lane = tl_ & 63, qi = lane & 15, kg = lane >> 4, sch = tl_ & 15, skey = tl_ >> 4;
; #pragma unroll
;                     for (int i = 0; i < 14; ++i) { const int kid = skey + 32 * i; *(LAS v4u*)(size_t)(IMG + kid * KPITCH + 16 * sch) = rst[i]; }
;                     if (tl_ < 15 * 31) rl[tl_] = rpb[h * 15 * 31 + tl_];
;                     __syncthreads();
;                     NA_LOADROWS(unit, rst, 2 * D);
.LBB0_3411:
	s_or_b64 exec, exec, s[0:1]
	s_add_i32 s0, s50, s53
	s_and_b32 s66, s0, 28
	v_add_u32_e32 v8, 64, v76
	v_add_u32_e32 v16, 0x80, v76
	v_add_u32_e32 v32, 0xc0, v76
	v_add_u32_e32 v48, 0x100, v76
	v_add_u32_e32 v56, 0x140, v76
	v_add_u32_e32 v66, 0x180, v76
	s_max_u32 s14, s66, 4
	v_med3_u32 v0, s66, 1, 25
	v_mul_hi_i32 v9, v8, s60
	v_mul_hi_i32 v17, v16, s60
	v_mul_hi_i32 v33, v32, s60
	v_mul_hi_i32 v49, v48, s60
	v_mul_hi_i32 v57, v56, s60
	v_mul_hi_i32 v67, v66, s60
	v_add_u32_e32 v2, 32, v76
	v_add_u32_e32 v10, 0x60, v76
	v_add_u32_e32 v18, 0xa0, v76
	v_add_u32_e32 v34, 0xe0, v76
	v_add_u32_e32 v50, 0x120, v76
	v_add_u32_e32 v58, 0x160, v76
	v_add_u32_e32 v68, 0x1a0, v76
	s_and_b32 s15, s40, 1
	s_lshl_b32 s0, s73, 8
	v_subrev_u32_e32 v0, s14, v0
	v_lshrrev_b32_e32 v11, 31, v9
	v_ashrrev_i32_e32 v9, 4, v9
	v_lshrrev_b32_e32 v19, 31, v17
	v_ashrrev_i32_e32 v17, 4, v17
	v_lshrrev_b32_e32 v35, 31, v33
	v_ashrrev_i32_e32 v33, 4, v33
	v_lshrrev_b32_e32 v51, 31, v49
	v_ashrrev_i32_e32 v49, 4, v49
	v_lshrrev_b32_e32 v59, 31, v57
	v_ashrrev_i32_e32 v57, 4, v57
	v_lshrrev_b32_e32 v71, 31, v67
	v_ashrrev_i32_e32 v67, 4, v67
	s_add_u32 s0, s46, s0
	v_add_u32_e32 v70, 10, v0
	v_mul_hi_i32 v0, v76, s60
	v_mul_hi_i32 v3, v2, s60
	v_add_u32_e32 v81, v9, v11
	v_mul_hi_i32 v11, v10, s60
	v_add_u32_e32 v85, v17, v19
	v_mul_hi_i32 v19, v18, s60
	v_add_u32_e32 v89, v33, v35
	v_mul_hi_i32 v35, v34, s60
	v_add_u32_e32 v93, v49, v51
	v_mul_hi_i32 v51, v50, s60
	v_add_u32_e32 v97, v57, v59
	v_mul_hi_i32 v59, v58, s60
	v_add_u32_e32 v102, v67, v71
	v_mul_hi_i32 v71, v68, s60
	s_addc_u32 s1, s47, 0
	v_lshrrev_b32_e32 v1, 31, v0
	v_ashrrev_i32_e32 v0, 4, v0
	v_lshrrev_b32_e32 v4, 31, v3
	v_ashrrev_i32_e32 v3, 4, v3
	v_lshrrev_b32_e32 v12, 31, v11
	v_ashrrev_i32_e32 v11, 4, v11
	v_lshrrev_b32_e32 v20, 31, v19
	v_ashrrev_i32_e32 v19, 4, v19
	v_lshrrev_b32_e32 v44, 31, v35
	v_ashrrev_i32_e32 v35, 4, v35
	v_lshrrev_b32_e32 v52, 31, v51
	v_ashrrev_i32_e32 v51, 4, v51
	v_lshrrev_b32_e32 v60, 31, v59
	v_ashrrev_i32_e32 v59, 4, v59
	v_lshrrev_b32_e32 v72, 31, v71
	v_ashrrev_i32_e32 v71, 4, v71
	v_lshl_add_u64 v[64:65], s[0:1], 0, v[104:105]
	s_add_i32 s0, s54, s57
	v_add_u32_e32 v77, v0, v1
	v_add_u32_e32 v79, v3, v4
	v_add_u32_e32 v83, v11, v12
	v_add_u32_e32 v87, v19, v20
	v_add_u32_e32 v91, v35, v44
	v_add_u32_e32 v95, v51, v52
	v_add_u32_e32 v100, v59, v60
	v_add_u32_e32 v113, v71, v72
	v_sub_u32_e64 v69, s66, 4 clamp
	s_and_b32 s8, s0, 0xfffff800
	s_mul_i32 s0, s15, 24
	v_min_i32_e32 v0, v77, v70
	v_min_i32_e32 v3, v79, v70
	v_min_i32_e32 v9, v81, v70
	v_min_i32_e32 v11, v83, v70
	v_min_i32_e32 v17, v85, v70
	v_min_i32_e32 v19, v87, v70
	v_min_i32_e32 v33, v89, v70
	v_min_i32_e32 v35, v91, v70
	v_min_i32_e32 v49, v93, v70
	v_min_i32_e32 v51, v95, v70
	v_min_i32_e32 v57, v97, v70
	v_min_i32_e32 v59, v100, v70
	v_min_i32_e32 v67, v102, v70
	v_min_i32_e32 v70, v113, v70
	s_or_b32 s16, s8, s0
	v_add_lshl_u32 v0, v0, v69, 6
	v_mad_i32_i24 v78, v77, s61, v76
	v_add_lshl_u32 v3, v3, v69, 6
	v_mad_i32_i24 v80, v79, s61, v2
	v_add_lshl_u32 v9, v9, v69, 6
	v_mad_i32_i24 v82, v81, s61, v8
	v_add_lshl_u32 v11, v11, v69, 6
	v_mad_i32_i24 v84, v83, s61, v10
	v_add_lshl_u32 v17, v17, v69, 6
	v_mad_i32_i24 v86, v85, s61, v16
	v_add_lshl_u32 v19, v19, v69, 6
	v_mad_i32_i24 v88, v87, s61, v18
	v_add_lshl_u32 v33, v33, v69, 6
	v_mad_i32_i24 v90, v89, s61, v32
	v_add_lshl_u32 v35, v35, v69, 6
	v_mad_i32_i24 v92, v91, s61, v34
	v_add_lshl_u32 v49, v49, v69, 6
	v_mad_i32_i24 v94, v93, s61, v48
	v_add_lshl_u32 v51, v51, v69, 6
	v_mad_i32_i24 v96, v95, s61, v50
	v_add_lshl_u32 v57, v57, v69, 6
	v_mad_i32_i24 v98, v97, s61, v56
	v_add_lshl_u32 v59, v59, v69, 6
	v_mad_i32_i24 v101, v100, s61, v58
	v_add_lshl_u32 v67, v67, v69, 6
	v_mad_i32_i24 v103, v102, s61, v66
	v_add_lshl_u32 v69, v70, v69, 6
	v_mad_i32_i24 v114, v113, s61, v68
	v_add3_u32 v0, v78, s16, v0
	v_add3_u32 v2, v80, s16, v3
	v_add3_u32 v8, v82, s16, v9
	v_add3_u32 v10, v84, s16, v11
	v_add3_u32 v16, v86, s16, v17
	v_add3_u32 v18, v88, s16, v19
	v_add3_u32 v32, v90, s16, v33
	v_add3_u32 v34, v92, s16, v35
	v_add3_u32 v48, v94, s16, v49
	v_add3_u32 v50, v96, s16, v51
	v_add3_u32 v56, v98, s16, v57
	v_add3_u32 v58, v101, s16, v59
	v_add3_u32 v66, v103, s16, v67
	v_add3_u32 v68, v114, s16, v69
	v_mad_i64_i32 v[0:1], s[0:1], v0, s62, v[64:65]
	v_mad_i64_i32 v[2:3], s[0:1], v2, s62, v[64:65]
	v_mad_i64_i32 v[8:9], s[0:1], v8, s62, v[64:65]
	v_mad_i64_i32 v[10:11], s[0:1], v10, s62, v[64:65]
	v_mad_i64_i32 v[16:17], s[0:1], v16, s62, v[64:65]
	v_mad_i64_i32 v[18:19], s[0:1], v18, s62, v[64:65]
	v_mad_i64_i32 v[32:33], s[0:1], v32, s62, v[64:65]
	v_mad_i64_i32 v[44:45], s[0:1], v34, s62, v[64:65]
	v_mad_i64_i32 v[48:49], s[0:1], v48, s62, v[64:65]
	v_mad_i64_i32 v[52:53], s[0:1], v50, s62, v[64:65]
	v_mad_i64_i32 v[56:57], s[0:1], v56, s62, v[64:65]
	v_mad_i64_i32 v[60:61], s[0:1], v58, s62, v[64:65]
	v_mad_i64_i32 v[66:67], s[0:1], v66, s62, v[64:65]
	v_mad_i64_i32 v[68:69], s[0:1], v68, s62, v[64:65]
	s_waitcnt lgkmcnt(0)
	s_barrier
; #define LAS __attribute__((address_space(3)))
; template <int L>
; __device__ __forceinline__ void layer_body(const Args& args, LAS unsigned char* lds, const int wave, const int G, const int gw, const int NGW, const int lo, const int hi,
;                                            unsigned char* const ws_kernel, const XcdBarrier& bar, int& pid) {
;     ...
;                     NA_LOADROWS(unit, rst, 2 * D);
;                     const int rr = wave >> 1, cb = 2 * hc + (wave & 1), r = rbase + rr, r0w = min(max(r - 4, 0), 24), cs = min(max(16 * cb - 8, 0), 32), coloff = cs - 24 * hc;
;                     const int c = 16 * cb + qi, wsq = min(max(c - 8, 0), 48);
;                     f32x4 sc[16];
; #pragma unroll
;                     for (int t = 0; t < 16; ++t) {
;                         const int irow = (r0w - krlo + (t >> 1)) * 40 + coloff + 16 * (t & 1);
;                         const unsigned ka = IMG + (unsigned)((irow + qi) * KPITCH + 16 * kg);
;                         f32x4 a = (f32x4){0.f, 0.f, 0.f, 0.f};
; #pragma unroll
;                         for (int ks = 0; ks < 4; ++ks) a = __builtin_amdgcn_mfma_f32_16x16x32_bf16(*(const LAS bf16x8*)(size_t)(ka + 64 * ks), qfn[ks], a, 0, 0, 0);
;                         const int dr = r0w + (t >> 1) - r + 7;
; #pragma unroll
;                         for (int j = 0; j < 4; ++j) { const int kc = cs + 16 * (t & 1) + 4 * kg + j; const bool valid = (kc >= wsq) && (kc < wsq + 16); const int dc = min(max(kc - c + 15, 0), 30);
;                             sc[t][j] = valid ? a[j] * scale_log2 + rl[dr * 31 + dc] * LOG2E : -1e30f; }
	global_load_dwordx4 v[4:7], v[0:1], off
	s_nop 0
	global_load_dwordx4 v[0:3], v[2:3], off
	s_nop 0
	global_load_dwordx4 v[12:15], v[8:9], off
	s_nop 0
	global_load_dwordx4 v[8:11], v[10:11], off
	s_nop 0
	global_load_dwordx4 v[20:23], v[16:17], off
	s_nop 0
	global_load_dwordx4 v[16:19], v[18:19], off
	s_nop 0
	global_load_dwordx4 v[32:35], v[32:33], off
	s_nop 0
	global_load_dwordx4 v[44:47], v[44:45], off
	s_nop 0
	global_load_dwordx4 v[48:51], v[48:49], off
	s_nop 0
	global_load_dwordx4 v[52:55], v[52:53], off
	s_nop 0
	global_load_dwordx4 v[56:59], v[56:57], off
	s_nop 0
	global_load_dwordx4 v[60:63], v[60:61], off
	s_nop 0
	global_load_dwordx4 v[64:67], v[66:67], off
	s_nop 0
	global_load_dwordx4 v[68:71], v[68:69], off
	s_add_i32 s66, s66, s42
	s_lshl_b32 s1, s15, 5
	s_max_i32 s0, s66, 4
	s_or_b32 s1, s1, s43
	s_add_i32 s0, s0, -4
	s_max_i32 s16, s1, 8
	s_min_u32 s0, s0, 24
	s_add_i32 s16, s16, -8
	s_min_u32 s16, s16, 32
	s_mulk_i32 s15, 0xffe8
	s_sub_i32 s76, s0, s14
	s_add_i32 s67, s16, s15
	s_mul_i32 s76, s76, 40
	v_bfe_u32 v99, v111, 4, 2
	v_add_u32_e32 v123, s67, v112
	s_add_i32 s68, s76, 0xa0
	v_lshl_add_u32 v118, v99, 4, 0
	v_add_u32_e32 v72, s68, v123
	v_mad_i32_i24 v104, v72, s58, v118
	ds_read_b128 v[72:75], v104
	ds_read_b128 v[124:127], v104 offset:64
	ds_read_b128 v[128:131], v104 offset:128
	s_waitcnt lgkmcnt(2)
	v_mfma_f32_16x16x32_bf16 v[72:75], v[72:75], v[24:27], 0
	ds_read_b128 v[136:139], v104 offset:192
	v_or_b32_e32 v110, s1, v112
	v_max_i32_e32 v109, 8, v110
	s_waitcnt lgkmcnt(2)
	v_mfma_f32_16x16x32_bf16 v[72:75], v[124:127], v[28:31], v[72:75]
	v_add_u32_e32 v104, -8, v109
	v_min_u32_e32 v126, 48, v104
	s_sub_i32 s0, s0, s66
	s_waitcnt lgkmcnt(1)
	v_mfma_f32_16x16x32_bf16 v[72:75], v[128:131], v[36:39], v[72:75]
	v_lshlrev_b32_e32 v109, 2, v99
	v_add_u32_e32 v134, s16, v109
	v_add_u32_e32 v128, 16, v126
	s_waitcnt lgkmcnt(0)
	v_mfma_f32_16x16x32_bf16 v[72:75], v[136:139], v[40:43], v[72:75]
	s_mulk_i32 s0, 0x7c
	s_add_i32 s77, s0, 0
	v_cmp_ge_u32_e32 vcc, v134, v126
	v_cmp_lt_u32_e64 s[0:1], v134, v128
	v_sub_u32_e32 v115, v134, v110
	s_add_i32 s77, s77, 0x1dc00
	s_and_b64 s[14:15], vcc, s[0:1]
	v_mov_b32_e32 v104, 0xf149f2ca
	v_max_i32_e32 v124, -15, v115
	v_mov_b32_e32 v115, 0xf149f2ca
	v_mov_b32_e32 v202, 0xf149f2ca
	s_nop 1
	v_add_u32_e32 v201, 15, v124
	v_min_u32_e32 v201, 30, v201
	v_lshl_add_u32 v213, v201, 2, s77
	ds_read_b32 v201, v213 offset:868
	v_mov_b32_e32 v200, v72
	s_waitcnt lgkmcnt(0)
	v_pk_mul_f32 v[200:201], v[200:201], s[12:13]
	s_nop 0
	v_add_f32_e32 v200, v200, v201
	v_cndmask_b32_e64 v115, v202, v200, s[14:15]
	v_or_b32_e32 v72, 1, v134
	v_cmp_ge_u32_e32 vcc, v72, v126
	v_cmp_lt_u32_e64 s[0:1], v72, v128
	v_sub_u32_e32 v72, v72, v110
	s_and_b64 s[16:17], vcc, s[0:1]
	v_max_i32_e32 v125, -15, v72
	s_nop 1
	v_add_u32_e32 v215, 15, v125
	v_min_u32_e32 v215, 30, v215
	v_lshl_add_u32 v220, v215, 2, s77
	ds_read_b32 v215, v220 offset:868
	v_mov_b32_e32 v214, v73
	s_waitcnt lgkmcnt(0)
	v_pk_mul_f32 v[214:215], v[214:215], s[12:13]
	s_nop 0
	v_add_f32_e32 v214, v214, v215
	v_cndmask_b32_e64 v104, v202, v214, s[16:17]
	v_or_b32_e32 v72, 2, v134
	v_cmp_ge_u32_e32 vcc, v72, v126
	v_cmp_lt_u32_e64 s[0:1], v72, v128
	v_sub_u32_e32 v72, v72, v110
	s_and_b64 s[20:21], vcc, s[0:1]
	v_mov_b32_e32 v116, 0xf149f2ca
	v_max_i32_e32 v127, -15, v72
	v_mov_b32_e32 v117, 0xf149f2ca
	s_nop 1
	v_add_u32_e32 v217, 15, v127
	v_min_u32_e32 v217, 30, v217
	v_lshl_add_u32 v221, v217, 2, s77
	ds_read_b32 v217, v221 offset:868
	v_mov_b32_e32 v216, v74
	s_waitcnt lgkmcnt(0)
	v_pk_mul_f32 v[216:217], v[216:217], s[12:13]
	s_nop 0
	v_add_f32_e32 v216, v216, v217
	v_cndmask_b32_e64 v117, v202, v216, s[20:21]
	v_or_b32_e32 v72, 3, v134
	v_cmp_ge_u32_e32 vcc, v72, v126
	v_cmp_lt_u32_e64 s[0:1], v72, v128
	v_sub_u32_e32 v72, v72, v110
	s_and_b64 s[22:23], vcc, s[0:1]
	v_max_i32_e32 v129, -15, v72
	s_nop 1
	v_add_u32_e32 v219, 15, v129
	v_min_u32_e32 v219, 30, v219
	v_lshl_add_u32 v222, v219, 2, s77
	ds_read_b32 v219, v222 offset:868
	v_mov_b32_e32 v218, v75
	s_waitcnt lgkmcnt(0)
	v_pk_mul_f32 v[218:219], v[218:219], s[12:13]
	s_nop 0
	v_add_f32_e32 v218, v218, v219
	v_cndmask_b32_e64 v116, v202, v218, s[22:23]
	v_add_u32_e32 v130, 16, v123
	v_add_u32_e32 v72, s68, v130
	v_mad_i32_i24 v119, v72, s58, v118
	ds_read_b128 v[72:75], v119
	ds_read_b128 v[136:139], v119 offset:64
	ds_read_b128 v[140:143], v119 offset:128
	v_add_u32_e32 v120, 16, v134
	v_cmp_lt_u32_e32 vcc, v134, v126
	s_waitcnt lgkmcnt(2)
	v_mfma_f32_16x16x32_bf16 v[72:75], v[72:75], v[24:27], 0
	v_cmp_ge_u32_e64 s[0:1], v120, v126
	v_sub_u32_e32 v120, v120, v110
	s_and_b64 s[24:25], s[0:1], vcc
	s_waitcnt lgkmcnt(1)
	v_mfma_f32_16x16x32_bf16 v[72:75], v[136:139], v[28:31], v[72:75]
	ds_read_b128 v[136:139], v119 offset:192
	v_mov_b32_e32 v119, 0xf149f2ca
	v_max_i32_e32 v131, -15, v120
	s_waitcnt lgkmcnt(1)
	v_mfma_f32_16x16x32_bf16 v[72:75], v[140:143], v[36:39], v[72:75]
	v_mov_b32_e32 v120, 0xf149f2ca
	s_waitcnt lgkmcnt(0)
	v_mfma_f32_16x16x32_bf16 v[72:75], v[136:139], v[40:43], v[72:75]
	s_nop 1
	v_add_u32_e32 v201, 15, v131
	v_min_u32_e32 v201, 30, v201
	v_lshl_add_u32 v223, v201, 2, s77
	ds_read_b32 v201, v223 offset:868
	s_nop 1
	v_mov_b32_e32 v200, v72
	s_waitcnt lgkmcnt(0)
	v_pk_mul_f32 v[200:201], v[200:201], s[12:13]
	s_nop 0
	v_add_f32_e32 v200, v200, v201
	v_cndmask_b32_e64 v120, v202, v200, s[24:25]
	s_nop 4
	v_add_u32_e32 v72, 17, v134
	v_cmp_ge_u32_e32 vcc, v72, v126
	v_cmp_lt_u32_e64 s[0:1], v72, v128
	v_sub_u32_e32 v72, v72, v110
	s_and_b64 s[26:27], vcc, s[0:1]
	v_max_i32_e32 v132, -15, v72
	s_nop 1
	v_add_u32_e32 v215, 15, v132
	v_min_u32_e32 v215, 30, v215
	v_lshl_add_u32 v224, v215, 2, s77
	ds_read_b32 v215, v224 offset:868
	v_mov_b32_e32 v214, v73
	s_waitcnt lgkmcnt(0)
; #define LAS __attribute__((address_space(3)))
; template <int L>
; __device__ __forceinline__ void layer_body(const Args& args, LAS unsigned char* lds, const int wave, const int G, const int gw, const int NGW, const int lo, const int hi,
;                                            unsigned char* const ws_kernel, const XcdBarrier& bar, int& pid) {
;     ...
;                     f32x4 sc[16];
; #pragma unroll
;                     for (int t = 0; t < 16; ++t) {
;                         const int irow = (r0w - krlo + (t >> 1)) * 40 + coloff + 16 * (t & 1);
;                         const unsigned ka = IMG + (unsigned)((irow + qi) * KPITCH + 16 * kg);
;                         f32x4 a = (f32x4){0.f, 0.f, 0.f, 0.f};
; #pragma unroll
;                         for (int ks = 0; ks < 4; ++ks) a = __builtin_amdgcn_mfma_f32_16x16x32_bf16(*(const LAS bf16x8*)(size_t)(ka + 64 * ks), qfn[ks], a, 0, 0, 0);
;                         const int dr = r0w + (t >> 1) - r + 7;
; #pragma unroll
;                         for (int j = 0; j < 4; ++j) { const int kc = cs + 16 * (t & 1) + 4 * kg + j; const bool valid = (kc >= wsq) && (kc < wsq + 16); const int dc = min(max(kc - c + 15, 0), 30);
;                             sc[t][j] = valid ? a[j] * scale_log2 + rl[dr * 31 + dc] * LOG2E : -1e30f; }
	v_pk_mul_f32 v[214:215], v[214:215], s[12:13]
	s_nop 0
	v_add_f32_e32 v214, v214, v215
	v_cndmask_b32_e64 v119, v202, v214, s[26:27]
	v_add_u32_e32 v72, 18, v134
	v_cmp_ge_u32_e32 vcc, v72, v126
	v_cmp_lt_u32_e64 s[0:1], v72, v128
	v_sub_u32_e32 v72, v72, v110
	s_and_b64 s[36:37], vcc, s[0:1]
	v_mov_b32_e32 v121, 0xf149f2ca
	v_max_i32_e32 v133, -15, v72
	v_mov_b32_e32 v122, 0xf149f2ca
	s_nop 1
	v_add_u32_e32 v217, 15, v133
	v_min_u32_e32 v217, 30, v217
	v_lshl_add_u32 v225, v217, 2, s77
	ds_read_b32 v217, v225 offset:868
	v_mov_b32_e32 v216, v74
	s_waitcnt lgkmcnt(0)
	v_pk_mul_f32 v[216:217], v[216:217], s[12:13]
	s_nop 0
	v_add_f32_e32 v216, v216, v217
	v_cndmask_b32_e64 v122, v202, v216, s[36:37]
	v_add_u32_e32 v72, 19, v134
	v_cmp_ge_u32_e32 vcc, v72, v126
	v_cmp_lt_u32_e64 s[0:1], v72, v128
	v_sub_u32_e32 v72, v72, v110
	s_and_b64 s[0:1], vcc, s[0:1]
	v_max_i32_e32 v134, -15, v72
	s_nop 1
	v_add_u32_e32 v219, 15, v134
	v_min_u32_e32 v219, 30, v219
	v_lshl_add_u32 v226, v219, 2, s77
	ds_read_b32 v219, v226 offset:868
	v_mov_b32_e32 v218, v75
	s_waitcnt lgkmcnt(0)
	v_pk_mul_f32 v[218:219], v[218:219], s[12:13]
	s_nop 0
	v_add_f32_e32 v218, v218, v219
	v_cndmask_b32_e64 v121, v202, v218, s[0:1]
	s_add_i32 s69, s76, 0xc8
	v_add_u32_e32 v72, s69, v123
	v_mad_i32_i24 v126, v72, s58, v118
	ds_read_b128 v[72:75], v126
	ds_read_b128 v[136:139], v126 offset:64
	ds_read_b128 v[140:143], v126 offset:128
	v_mov_b32_e32 v128, 0xf149f2ca
	s_waitcnt lgkmcnt(2)
	v_mfma_f32_16x16x32_bf16 v[72:75], v[72:75], v[24:27], 0
	s_waitcnt lgkmcnt(1)
	v_mfma_f32_16x16x32_bf16 v[72:75], v[136:139], v[28:31], v[72:75]
	ds_read_b128 v[136:139], v126 offset:192
	v_mov_b32_e32 v126, 0xf149f2ca
	s_waitcnt lgkmcnt(1)
	v_mfma_f32_16x16x32_bf16 v[72:75], v[140:143], v[36:39], v[72:75]
	s_waitcnt lgkmcnt(0)
	v_mfma_f32_16x16x32_bf16 v[72:75], v[136:139], v[40:43], v[72:75]
	ds_read_b32 v201, v213 offset:992
	ds_read_b32 v215, v220 offset:992
	ds_read_b32 v217, v221 offset:992
	ds_read_b32 v219, v222 offset:992
	s_nop 4
	v_mov_b32_e32 v200, v72
	v_mov_b32_e32 v214, v73
	v_mov_b32_e32 v216, v74
	v_mov_b32_e32 v218, v75
	s_waitcnt lgkmcnt(0)
	v_pk_mul_f32 v[200:201], v[200:201], s[12:13]
	v_pk_mul_f32 v[214:215], v[214:215], s[12:13]
	v_pk_mul_f32 v[216:217], v[216:217], s[12:13]
	v_pk_mul_f32 v[218:219], v[218:219], s[12:13]
	v_add_f32_e32 v200, v200, v201
	v_add_f32_e32 v214, v214, v215
	v_add_f32_e32 v216, v216, v217
	v_add_f32_e32 v218, v218, v219
	v_cndmask_b32_e64 v128, v202, v200, s[14:15]
	v_cndmask_b32_e64 v126, v202, v214, s[16:17]
	v_cndmask_b32_e64 v136, v202, v216, s[20:21]
	v_cndmask_b32_e64 v135, v202, v218, s[22:23]
	v_add_u32_e32 v72, s69, v130
	v_mad_i32_i24 v137, v72, s58, v118
	ds_read_b128 v[72:75], v137
	ds_read_b128 v[138:141], v137 offset:64
	ds_read_b128 v[142:145], v137 offset:128
	s_waitcnt lgkmcnt(2)
	v_mfma_f32_16x16x32_bf16 v[72:75], v[72:75], v[24:27], 0
	s_waitcnt lgkmcnt(1)
	v_mfma_f32_16x16x32_bf16 v[72:75], v[138:141], v[28:31], v[72:75]
	ds_read_b128 v[138:141], v137 offset:192
	v_mov_b32_e32 v137, 0xf149f2ca
	s_waitcnt lgkmcnt(1)
	v_mfma_f32_16x16x32_bf16 v[72:75], v[142:145], v[36:39], v[72:75]
	s_waitcnt lgkmcnt(0)
	v_mfma_f32_16x16x32_bf16 v[72:75], v[138:141], v[40:43], v[72:75]
	v_mov_b32_e32 v138, 0xf149f2ca
	ds_read_b32 v201, v223 offset:992
	ds_read_b32 v215, v224 offset:992
	ds_read_b32 v217, v225 offset:992
	ds_read_b32 v219, v226 offset:992
	s_nop 4
	v_mov_b32_e32 v200, v72
	v_mov_b32_e32 v214, v73
	v_mov_b32_e32 v216, v74
	v_mov_b32_e32 v218, v75
	s_waitcnt lgkmcnt(0)
	v_pk_mul_f32 v[200:201], v[200:201], s[12:13]
	v_pk_mul_f32 v[214:215], v[214:215], s[12:13]
	v_pk_mul_f32 v[216:217], v[216:217], s[12:13]
	v_pk_mul_f32 v[218:219], v[218:219], s[12:13]
	v_add_f32_e32 v200, v200, v201
	v_add_f32_e32 v214, v214, v215
	v_add_f32_e32 v216, v216, v217
	v_add_f32_e32 v218, v218, v219
	v_cndmask_b32_e64 v138, v202, v200, s[24:25]
	v_cndmask_b32_e64 v137, v202, v214, s[26:27]
	v_cndmask_b32_e64 v140, v202, v216, s[36:37]
	v_cndmask_b32_e64 v139, v202, v218, s[0:1]
	s_add_i32 s70, s76, 0xf0
	v_add_u32_e32 v72, s70, v123
	v_mad_i32_i24 v141, v72, s58, v118
	ds_read_b128 v[72:75], v141
	ds_read_b128 v[142:145], v141 offset:64
	ds_read_b128 v[146:149], v141 offset:128
	s_waitcnt lgkmcnt(2)
	v_mfma_f32_16x16x32_bf16 v[72:75], v[72:75], v[24:27], 0
	s_waitcnt lgkmcnt(1)
	v_mfma_f32_16x16x32_bf16 v[72:75], v[142:145], v[28:31], v[72:75]
	ds_read_b128 v[142:145], v141 offset:192
	v_mov_b32_e32 v141, 0xf149f2ca
	s_waitcnt lgkmcnt(1)
	v_mfma_f32_16x16x32_bf16 v[72:75], v[146:149], v[36:39], v[72:75]
	s_waitcnt lgkmcnt(0)
	v_mfma_f32_16x16x32_bf16 v[72:75], v[142:145], v[40:43], v[72:75]
	v_mov_b32_e32 v142, 0xf149f2ca
	ds_read_b32 v201, v213 offset:1116
	ds_read_b32 v215, v220 offset:1116
	ds_read_b32 v217, v221 offset:1116
	ds_read_b32 v219, v222 offset:1116
	s_nop 4
	v_mov_b32_e32 v200, v72
	v_mov_b32_e32 v214, v73
	v_mov_b32_e32 v216, v74
	v_mov_b32_e32 v218, v75
	s_waitcnt lgkmcnt(0)
	v_pk_mul_f32 v[200:201], v[200:201], s[12:13]
	v_pk_mul_f32 v[214:215], v[214:215], s[12:13]
	v_pk_mul_f32 v[216:217], v[216:217], s[12:13]
	v_pk_mul_f32 v[218:219], v[218:219], s[12:13]
	v_add_f32_e32 v200, v200, v201
	v_add_f32_e32 v214, v214, v215
	v_add_f32_e32 v216, v216, v217
	v_add_f32_e32 v218, v218, v219
	v_cndmask_b32_e64 v142, v202, v200, s[14:15]
	v_cndmask_b32_e64 v141, v202, v214, s[16:17]
	v_cndmask_b32_e64 v144, v202, v216, s[20:21]
	v_cndmask_b32_e64 v143, v202, v218, s[22:23]
	v_add_u32_e32 v72, s70, v130
	v_mad_i32_i24 v145, v72, s58, v118
	ds_read_b128 v[72:75], v145
	ds_read_b128 v[146:149], v145 offset:64
	ds_read_b128 v[150:153], v145 offset:128
	s_waitcnt lgkmcnt(2)
; #define LAS __attribute__((address_space(3)))
; template <int L>
; __device__ __forceinline__ void layer_body(const Args& args, LAS unsigned char* lds, const int wave, const int G, const int gw, const int NGW, const int lo, const int hi,
;                                            unsigned char* const ws_kernel, const XcdBarrier& bar, int& pid) {
;     ...
;                     f32x4 sc[16];
; #pragma unroll
;                     for (int t = 0; t < 16; ++t) {
;                         const int irow = (r0w - krlo + (t >> 1)) * 40 + coloff + 16 * (t & 1);
;                         const unsigned ka = IMG + (unsigned)((irow + qi) * KPITCH + 16 * kg);
;                         f32x4 a = (f32x4){0.f, 0.f, 0.f, 0.f};
; #pragma unroll
;                         for (int ks = 0; ks < 4; ++ks) a = __builtin_amdgcn_mfma_f32_16x16x32_bf16(*(const LAS bf16x8*)(size_t)(ka + 64 * ks), qfn[ks], a, 0, 0, 0);
;                         const int dr = r0w + (t >> 1) - r + 7;
; #pragma unroll
;                         for (int j = 0; j < 4; ++j) { const int kc = cs + 16 * (t & 1) + 4 * kg + j; const bool valid = (kc >= wsq) && (kc < wsq + 16); const int dc = min(max(kc - c + 15, 0), 30);
;                             sc[t][j] = valid ? a[j] * scale_log2 + rl[dr * 31 + dc] * LOG2E : -1e30f; }
	v_mfma_f32_16x16x32_bf16 v[72:75], v[72:75], v[24:27], 0
	s_waitcnt lgkmcnt(1)
	v_mfma_f32_16x16x32_bf16 v[72:75], v[146:149], v[28:31], v[72:75]
	ds_read_b128 v[146:149], v145 offset:192
	v_mov_b32_e32 v145, 0xf149f2ca
	s_waitcnt lgkmcnt(1)
	v_mfma_f32_16x16x32_bf16 v[72:75], v[150:153], v[36:39], v[72:75]
	s_waitcnt lgkmcnt(0)
	v_mfma_f32_16x16x32_bf16 v[72:75], v[146:149], v[40:43], v[72:75]
	v_mov_b32_e32 v146, 0xf149f2ca
	ds_read_b32 v201, v223 offset:1116
	ds_read_b32 v215, v224 offset:1116
	ds_read_b32 v217, v225 offset:1116
	ds_read_b32 v219, v226 offset:1116
	s_nop 4
	v_mov_b32_e32 v200, v72
	v_mov_b32_e32 v214, v73
	v_mov_b32_e32 v216, v74
	v_mov_b32_e32 v218, v75
	s_waitcnt lgkmcnt(0)
	v_pk_mul_f32 v[200:201], v[200:201], s[12:13]
	v_pk_mul_f32 v[214:215], v[214:215], s[12:13]
	v_pk_mul_f32 v[216:217], v[216:217], s[12:13]
	v_pk_mul_f32 v[218:219], v[218:219], s[12:13]
	v_add_f32_e32 v200, v200, v201
	v_add_f32_e32 v214, v214, v215
	v_add_f32_e32 v216, v216, v217
	v_add_f32_e32 v218, v218, v219
	v_cndmask_b32_e64 v146, v202, v200, s[24:25]
	v_cndmask_b32_e64 v145, v202, v214, s[26:27]
	v_cndmask_b32_e64 v148, v202, v216, s[36:37]
	v_cndmask_b32_e64 v147, v202, v218, s[0:1]
	s_add_i32 s71, s76, 0x118
	v_add_u32_e32 v72, s71, v123
	v_mad_i32_i24 v149, v72, s58, v118
	ds_read_b128 v[72:75], v149
	ds_read_b128 v[150:153], v149 offset:64
	ds_read_b128 v[154:157], v149 offset:128
	s_waitcnt lgkmcnt(2)
	v_mfma_f32_16x16x32_bf16 v[72:75], v[72:75], v[24:27], 0
	s_waitcnt lgkmcnt(1)
	v_mfma_f32_16x16x32_bf16 v[72:75], v[150:153], v[28:31], v[72:75]
	ds_read_b128 v[150:153], v149 offset:192
	v_mov_b32_e32 v149, 0xf149f2ca
	s_waitcnt lgkmcnt(1)
	v_mfma_f32_16x16x32_bf16 v[72:75], v[154:157], v[36:39], v[72:75]
	s_waitcnt lgkmcnt(0)
	v_mfma_f32_16x16x32_bf16 v[72:75], v[150:153], v[40:43], v[72:75]
	v_mov_b32_e32 v150, 0xf149f2ca
	ds_read_b32 v201, v213 offset:1240
	ds_read_b32 v215, v220 offset:1240
	ds_read_b32 v217, v221 offset:1240
	ds_read_b32 v219, v222 offset:1240
	s_nop 4
	v_mov_b32_e32 v200, v72
	v_mov_b32_e32 v214, v73
	v_mov_b32_e32 v216, v74
	v_mov_b32_e32 v218, v75
	s_waitcnt lgkmcnt(0)
	v_pk_mul_f32 v[200:201], v[200:201], s[12:13]
	v_pk_mul_f32 v[214:215], v[214:215], s[12:13]
	v_pk_mul_f32 v[216:217], v[216:217], s[12:13]
	v_pk_mul_f32 v[218:219], v[218:219], s[12:13]
	v_add_f32_e32 v200, v200, v201
	v_add_f32_e32 v214, v214, v215
	v_add_f32_e32 v216, v216, v217
	v_add_f32_e32 v218, v218, v219
	v_cndmask_b32_e64 v150, v202, v200, s[14:15]
	v_cndmask_b32_e64 v149, v202, v214, s[16:17]
	v_cndmask_b32_e64 v152, v202, v216, s[20:21]
	v_cndmask_b32_e64 v151, v202, v218, s[22:23]
	v_add_u32_e32 v72, s71, v130
	v_mad_i32_i24 v153, v72, s58, v118
	ds_read_b128 v[72:75], v153
	ds_read_b128 v[154:157], v153 offset:64
	ds_read_b128 v[158:161], v153 offset:128
	s_waitcnt lgkmcnt(2)
	v_mfma_f32_16x16x32_bf16 v[72:75], v[72:75], v[24:27], 0
	s_waitcnt lgkmcnt(1)
	v_mfma_f32_16x16x32_bf16 v[72:75], v[154:157], v[28:31], v[72:75]
	ds_read_b128 v[154:157], v153 offset:192
	v_mov_b32_e32 v153, 0xf149f2ca
	s_waitcnt lgkmcnt(1)
	v_mfma_f32_16x16x32_bf16 v[72:75], v[158:161], v[36:39], v[72:75]
	s_waitcnt lgkmcnt(0)
	v_mfma_f32_16x16x32_bf16 v[72:75], v[154:157], v[40:43], v[72:75]
	v_mov_b32_e32 v154, 0xf149f2ca
	ds_read_b32 v201, v223 offset:1240
	ds_read_b32 v215, v224 offset:1240
	ds_read_b32 v217, v225 offset:1240
	ds_read_b32 v219, v226 offset:1240
	s_nop 4
	v_mov_b32_e32 v200, v72
	v_mov_b32_e32 v214, v73
	v_mov_b32_e32 v216, v74
	v_mov_b32_e32 v218, v75
	s_waitcnt lgkmcnt(0)
	v_pk_mul_f32 v[200:201], v[200:201], s[12:13]
	v_pk_mul_f32 v[214:215], v[214:215], s[12:13]
	v_pk_mul_f32 v[216:217], v[216:217], s[12:13]
	v_pk_mul_f32 v[218:219], v[218:219], s[12:13]
	v_add_f32_e32 v200, v200, v201
	v_add_f32_e32 v214, v214, v215
	v_add_f32_e32 v216, v216, v217
	v_add_f32_e32 v218, v218, v219
	v_cndmask_b32_e64 v154, v202, v200, s[24:25]
	v_cndmask_b32_e64 v153, v202, v214, s[26:27]
	v_cndmask_b32_e64 v156, v202, v216, s[36:37]
	v_cndmask_b32_e64 v155, v202, v218, s[0:1]
	s_add_i32 s72, s76, 0x140
	v_add_u32_e32 v72, s72, v123
	v_mad_i32_i24 v157, v72, s58, v118
	ds_read_b128 v[72:75], v157
	ds_read_b128 v[158:161], v157 offset:64
	ds_read_b128 v[162:165], v157 offset:128
	s_waitcnt lgkmcnt(2)
	v_mfma_f32_16x16x32_bf16 v[72:75], v[72:75], v[24:27], 0
	s_waitcnt lgkmcnt(1)
	v_mfma_f32_16x16x32_bf16 v[72:75], v[158:161], v[28:31], v[72:75]
	ds_read_b128 v[158:161], v157 offset:192
	v_mov_b32_e32 v157, 0xf149f2ca
	s_waitcnt lgkmcnt(1)
	v_mfma_f32_16x16x32_bf16 v[72:75], v[162:165], v[36:39], v[72:75]
	s_waitcnt lgkmcnt(0)
	v_mfma_f32_16x16x32_bf16 v[72:75], v[158:161], v[40:43], v[72:75]
	v_mov_b32_e32 v158, 0xf149f2ca
	ds_read_b32 v201, v213 offset:1364
	ds_read_b32 v215, v220 offset:1364
	ds_read_b32 v217, v221 offset:1364
	ds_read_b32 v219, v222 offset:1364
	s_nop 4
	v_mov_b32_e32 v200, v72
	v_mov_b32_e32 v214, v73
	v_mov_b32_e32 v216, v74
	v_mov_b32_e32 v218, v75
	s_waitcnt lgkmcnt(0)
	v_pk_mul_f32 v[200:201], v[200:201], s[12:13]
	v_pk_mul_f32 v[214:215], v[214:215], s[12:13]
	v_pk_mul_f32 v[216:217], v[216:217], s[12:13]
	v_pk_mul_f32 v[218:219], v[218:219], s[12:13]
	v_add_f32_e32 v200, v200, v201
	v_add_f32_e32 v214, v214, v215
	v_add_f32_e32 v216, v216, v217
	v_add_f32_e32 v218, v218, v219
	v_cndmask_b32_e64 v158, v202, v200, s[14:15]
	v_cndmask_b32_e64 v157, v202, v214, s[16:17]
	v_cndmask_b32_e64 v160, v202, v216, s[20:21]
	v_cndmask_b32_e64 v159, v202, v218, s[22:23]
	v_add_u32_e32 v72, s72, v130
	v_mad_i32_i24 v161, v72, s58, v118
	ds_read_b128 v[72:75], v161
	ds_read_b128 v[162:165], v161 offset:64
	ds_read_b128 v[166:169], v161 offset:128
	s_waitcnt lgkmcnt(2)
; #define LAS __attribute__((address_space(3)))
; template <int L>
; __device__ __forceinline__ void layer_body(const Args& args, LAS unsigned char* lds, const int wave, const int G, const int gw, const int NGW, const int lo, const int hi,
;                                            unsigned char* const ws_kernel, const XcdBarrier& bar, int& pid) {
;     ...
;                     f32x4 sc[16];
; #pragma unroll
;                     for (int t = 0; t < 16; ++t) {
;                         const int irow = (r0w - krlo + (t >> 1)) * 40 + coloff + 16 * (t & 1);
;                         const unsigned ka = IMG + (unsigned)((irow + qi) * KPITCH + 16 * kg);
;                         f32x4 a = (f32x4){0.f, 0.f, 0.f, 0.f};
; #pragma unroll
;                         for (int ks = 0; ks < 4; ++ks) a = __builtin_amdgcn_mfma_f32_16x16x32_bf16(*(const LAS bf16x8*)(size_t)(ka + 64 * ks), qfn[ks], a, 0, 0, 0);
;                         const int dr = r0w + (t >> 1) - r + 7;
; #pragma unroll
;                         for (int j = 0; j < 4; ++j) { const int kc = cs + 16 * (t & 1) + 4 * kg + j; const bool valid = (kc >= wsq) && (kc < wsq + 16); const int dc = min(max(kc - c + 15, 0), 30);
;                             sc[t][j] = valid ? a[j] * scale_log2 + rl[dr * 31 + dc] * LOG2E : -1e30f; }
	v_mfma_f32_16x16x32_bf16 v[72:75], v[72:75], v[24:27], 0
	s_waitcnt lgkmcnt(1)
	v_mfma_f32_16x16x32_bf16 v[72:75], v[162:165], v[28:31], v[72:75]
	ds_read_b128 v[162:165], v161 offset:192
	v_mov_b32_e32 v161, 0xf149f2ca
	s_waitcnt lgkmcnt(1)
	v_mfma_f32_16x16x32_bf16 v[72:75], v[166:169], v[36:39], v[72:75]
	s_waitcnt lgkmcnt(0)
	v_mfma_f32_16x16x32_bf16 v[72:75], v[162:165], v[40:43], v[72:75]
	v_mov_b32_e32 v162, 0xf149f2ca
	ds_read_b32 v201, v223 offset:1364
	ds_read_b32 v215, v224 offset:1364
	ds_read_b32 v217, v225 offset:1364
	ds_read_b32 v219, v226 offset:1364
	s_nop 4
	v_mov_b32_e32 v200, v72
	v_mov_b32_e32 v214, v73
	v_mov_b32_e32 v216, v74
	v_mov_b32_e32 v218, v75
	s_waitcnt lgkmcnt(0)
	v_pk_mul_f32 v[200:201], v[200:201], s[12:13]
	v_pk_mul_f32 v[214:215], v[214:215], s[12:13]
	v_pk_mul_f32 v[216:217], v[216:217], s[12:13]
	v_pk_mul_f32 v[218:219], v[218:219], s[12:13]
	v_add_f32_e32 v200, v200, v201
	v_add_f32_e32 v214, v214, v215
	v_add_f32_e32 v216, v216, v217
	v_add_f32_e32 v218, v218, v219
	v_cndmask_b32_e64 v162, v202, v200, s[24:25]
	v_cndmask_b32_e64 v161, v202, v214, s[26:27]
	v_cndmask_b32_e64 v164, v202, v216, s[36:37]
	v_cndmask_b32_e64 v163, v202, v218, s[0:1]
	s_add_i32 s74, s76, 0x168
	v_add_u32_e32 v72, s74, v123
	v_mad_i32_i24 v165, v72, s58, v118
	ds_read_b128 v[72:75], v165
	ds_read_b128 v[166:169], v165 offset:64
	ds_read_b128 v[170:173], v165 offset:128
	s_waitcnt lgkmcnt(2)
	v_mfma_f32_16x16x32_bf16 v[72:75], v[72:75], v[24:27], 0
	s_waitcnt lgkmcnt(1)
	v_mfma_f32_16x16x32_bf16 v[72:75], v[166:169], v[28:31], v[72:75]
	ds_read_b128 v[166:169], v165 offset:192
	v_mov_b32_e32 v165, 0xf149f2ca
	s_waitcnt lgkmcnt(1)
	v_mfma_f32_16x16x32_bf16 v[72:75], v[170:173], v[36:39], v[72:75]
	s_waitcnt lgkmcnt(0)
	v_mfma_f32_16x16x32_bf16 v[72:75], v[166:169], v[40:43], v[72:75]
	v_mov_b32_e32 v166, 0xf149f2ca
	ds_read_b32 v201, v213 offset:1488
	ds_read_b32 v215, v220 offset:1488
	ds_read_b32 v217, v221 offset:1488
	ds_read_b32 v219, v222 offset:1488
	s_nop 4
	v_mov_b32_e32 v200, v72
	v_mov_b32_e32 v214, v73
	v_mov_b32_e32 v216, v74
	v_mov_b32_e32 v218, v75
	s_waitcnt lgkmcnt(0)
	v_pk_mul_f32 v[200:201], v[200:201], s[12:13]
	v_pk_mul_f32 v[214:215], v[214:215], s[12:13]
	v_pk_mul_f32 v[216:217], v[216:217], s[12:13]
	v_pk_mul_f32 v[218:219], v[218:219], s[12:13]
	v_add_f32_e32 v200, v200, v201
	v_add_f32_e32 v214, v214, v215
	v_add_f32_e32 v216, v216, v217
	v_add_f32_e32 v218, v218, v219
	v_cndmask_b32_e64 v166, v202, v200, s[14:15]
	v_cndmask_b32_e64 v165, v202, v214, s[16:17]
	v_cndmask_b32_e64 v168, v202, v216, s[20:21]
	v_cndmask_b32_e64 v167, v202, v218, s[22:23]
	v_add_u32_e32 v72, s74, v130
	v_mad_i32_i24 v169, v72, s58, v118
	ds_read_b128 v[72:75], v169
	ds_read_b128 v[170:173], v169 offset:64
	ds_read_b128 v[174:177], v169 offset:128
	s_waitcnt lgkmcnt(2)
	v_mfma_f32_16x16x32_bf16 v[72:75], v[72:75], v[24:27], 0
	s_waitcnt lgkmcnt(1)
	v_mfma_f32_16x16x32_bf16 v[72:75], v[170:173], v[28:31], v[72:75]
	ds_read_b128 v[170:173], v169 offset:192
	v_mov_b32_e32 v169, 0xf149f2ca
	s_waitcnt lgkmcnt(1)
	v_mfma_f32_16x16x32_bf16 v[72:75], v[174:177], v[36:39], v[72:75]
	s_waitcnt lgkmcnt(0)
	v_mfma_f32_16x16x32_bf16 v[72:75], v[170:173], v[40:43], v[72:75]
	v_mov_b32_e32 v170, 0xf149f2ca
	ds_read_b32 v201, v223 offset:1488
	ds_read_b32 v215, v224 offset:1488
	ds_read_b32 v217, v225 offset:1488
	ds_read_b32 v219, v226 offset:1488
	s_nop 4
	v_mov_b32_e32 v200, v72
	v_mov_b32_e32 v214, v73
	v_mov_b32_e32 v216, v74
	v_mov_b32_e32 v218, v75
	s_waitcnt lgkmcnt(0)
	v_pk_mul_f32 v[200:201], v[200:201], s[12:13]
	v_pk_mul_f32 v[214:215], v[214:215], s[12:13]
	v_pk_mul_f32 v[216:217], v[216:217], s[12:13]
	v_pk_mul_f32 v[218:219], v[218:219], s[12:13]
	v_add_f32_e32 v200, v200, v201
	v_add_f32_e32 v214, v214, v215
	v_add_f32_e32 v216, v216, v217
	v_add_f32_e32 v218, v218, v219
	v_cndmask_b32_e64 v170, v202, v200, s[24:25]
	v_cndmask_b32_e64 v169, v202, v214, s[26:27]
	v_cndmask_b32_e64 v172, v202, v216, s[36:37]
	v_cndmask_b32_e64 v171, v202, v218, s[0:1]
	s_add_i32 s75, s76, 0x190
	v_add_u32_e32 v72, s75, v123
	v_mad_i32_i24 v173, v72, s58, v118
	ds_read_b128 v[72:75], v173
	ds_read_b128 v[174:177], v173 offset:64
	ds_read_b128 v[178:181], v173 offset:128
	s_waitcnt lgkmcnt(2)
	v_mfma_f32_16x16x32_bf16 v[72:75], v[72:75], v[24:27], 0
	s_waitcnt lgkmcnt(1)
	v_mfma_f32_16x16x32_bf16 v[72:75], v[174:177], v[28:31], v[72:75]
	ds_read_b128 v[174:177], v173 offset:192
	v_mov_b32_e32 v173, 0xf149f2ca
	s_waitcnt lgkmcnt(1)
	v_mfma_f32_16x16x32_bf16 v[72:75], v[178:181], v[36:39], v[72:75]
	s_waitcnt lgkmcnt(0)
	v_mfma_f32_16x16x32_bf16 v[72:75], v[174:177], v[40:43], v[72:75]
	v_mov_b32_e32 v174, 0xf149f2ca
	ds_read_b32 v201, v213 offset:1612
	ds_read_b32 v215, v220 offset:1612
	ds_read_b32 v217, v221 offset:1612
	ds_read_b32 v219, v222 offset:1612
	s_nop 4
	v_mov_b32_e32 v200, v72
	v_mov_b32_e32 v214, v73
	v_mov_b32_e32 v216, v74
	v_mov_b32_e32 v218, v75
	s_waitcnt lgkmcnt(0)
	v_pk_mul_f32 v[200:201], v[200:201], s[12:13]
	v_pk_mul_f32 v[214:215], v[214:215], s[12:13]
	v_pk_mul_f32 v[216:217], v[216:217], s[12:13]
	v_pk_mul_f32 v[218:219], v[218:219], s[12:13]
	v_add_f32_e32 v200, v200, v201
	v_add_f32_e32 v214, v214, v215
	v_add_f32_e32 v216, v216, v217
	v_add_f32_e32 v218, v218, v219
	v_cndmask_b32_e64 v174, v202, v200, s[14:15]
	v_cndmask_b32_e64 v173, v202, v214, s[16:17]
	v_cndmask_b32_e64 v176, v202, v216, s[20:21]
	v_cndmask_b32_e64 v175, v202, v218, s[22:23]
	v_add_u32_e32 v72, s75, v130
	v_mad_i32_i24 v177, v72, s58, v118
	ds_read_b128 v[72:75], v177
	ds_read_b128 v[178:181], v177 offset:64
	ds_read_b128 v[182:185], v177 offset:128
	s_waitcnt lgkmcnt(2)
; #define LAS __attribute__((address_space(3)))
; template <int L>
; __device__ __forceinline__ void layer_body(const Args& args, LAS unsigned char* lds, const int wave, const int G, const int gw, const int NGW, const int lo, const int hi,
;                                            unsigned char* const ws_kernel, const XcdBarrier& bar, int& pid) {
;     ...
;                     f32x4 sc[16];
; #pragma unroll
;                     for (int t = 0; t < 16; ++t) {
;                         const int irow = (r0w - krlo + (t >> 1)) * 40 + coloff + 16 * (t & 1);
;                         const unsigned ka = IMG + (unsigned)((irow + qi) * KPITCH + 16 * kg);
;                         f32x4 a = (f32x4){0.f, 0.f, 0.f, 0.f};
; #pragma unroll
;                         for (int ks = 0; ks < 4; ++ks) a = __builtin_amdgcn_mfma_f32_16x16x32_bf16(*(const LAS bf16x8*)(size_t)(ka + 64 * ks), qfn[ks], a, 0, 0, 0);
;                         const int dr = r0w + (t >> 1) - r + 7;
; #pragma unroll
;                         for (int j = 0; j < 4; ++j) { const int kc = cs + 16 * (t & 1) + 4 * kg + j; const bool valid = (kc >= wsq) && (kc < wsq + 16); const int dc = min(max(kc - c + 15, 0), 30);
;                             sc[t][j] = valid ? a[j] * scale_log2 + rl[dr * 31 + dc] * LOG2E : -1e30f; }
;                         __builtin_amdgcn_sched_barrier(0);
;                     }
;                     float mx = -1e30f;
; #pragma unroll
;                     for (int t = 0; t < 16; ++t)
; #pragma unroll
;                         for (int j = 0; j < 4; ++j) mx = fmaxf(mx, sc[t][j]);
;                     mx = fmaxf(mx, __shfl_xor(mx, 16)); mx = fmaxf(mx, __shfl_xor(mx, 32));
	v_mfma_f32_16x16x32_bf16 v[72:75], v[72:75], v[24:27], 0
	s_waitcnt lgkmcnt(1)
	v_mfma_f32_16x16x32_bf16 v[72:75], v[178:181], v[28:31], v[72:75]
	ds_read_b128 v[178:181], v177 offset:192
	s_waitcnt lgkmcnt(1)
	v_mfma_f32_16x16x32_bf16 v[72:75], v[182:185], v[36:39], v[72:75]
	v_mov_b32_e32 v183, 0xf149f2ca
	s_waitcnt lgkmcnt(0)
	v_mfma_f32_16x16x32_bf16 v[72:75], v[178:181], v[40:43], v[72:75]
	v_mov_b32_e32 v181, 0xf149f2ca
	ds_read_b32 v201, v223 offset:1612
	ds_read_b32 v215, v224 offset:1612
	ds_read_b32 v217, v225 offset:1612
	ds_read_b32 v219, v226 offset:1612
	s_nop 4
	v_mov_b32_e32 v200, v72
	v_mov_b32_e32 v214, v73
	v_mov_b32_e32 v216, v74
	v_mov_b32_e32 v218, v75
	s_waitcnt lgkmcnt(0)
	v_pk_mul_f32 v[200:201], v[200:201], s[12:13]
	v_pk_mul_f32 v[214:215], v[214:215], s[12:13]
	v_pk_mul_f32 v[216:217], v[216:217], s[12:13]
	v_pk_mul_f32 v[218:219], v[218:219], s[12:13]
	v_add_f32_e32 v200, v200, v201
	v_add_f32_e32 v214, v214, v215
	v_add_f32_e32 v216, v216, v217
	v_add_f32_e32 v218, v218, v219
	v_cndmask_b32_e64 v183, v202, v200, s[24:25]
	v_cndmask_b32_e64 v181, v202, v214, s[26:27]
	v_cndmask_b32_e64 v204, v202, v216, s[36:37]
	v_cndmask_b32_e64 v203, v202, v218, s[0:1]
	s_addk_i32 s76, 0x1b8
	v_add_u32_e32 v72, s76, v123
	v_mad_i32_i24 v123, v72, s58, v118
	ds_read_b128 v[72:75], v123
	ds_read_b128 v[184:187], v123 offset:64
	ds_read_b128 v[188:191], v123 offset:128
	v_mov_b32_e32 v205, 0xf149f2ca
	v_mov_b32_e32 v206, 0xf149f2ca
	s_waitcnt lgkmcnt(2)
	v_mfma_f32_16x16x32_bf16 v[72:75], v[72:75], v[24:27], 0
	s_waitcnt lgkmcnt(1)
	v_mfma_f32_16x16x32_bf16 v[72:75], v[184:187], v[28:31], v[72:75]
	ds_read_b128 v[184:187], v123 offset:192
	s_waitcnt lgkmcnt(1)
	v_mfma_f32_16x16x32_bf16 v[72:75], v[188:191], v[36:39], v[72:75]
	s_waitcnt lgkmcnt(0)
	v_mfma_f32_16x16x32_bf16 v[72:75], v[184:187], v[40:43], v[72:75]
	ds_read_b32 v201, v213 offset:1736
	ds_read_b32 v215, v220 offset:1736
	ds_read_b32 v217, v221 offset:1736
	ds_read_b32 v219, v222 offset:1736
	s_nop 4
	v_mov_b32_e32 v200, v72
	v_mov_b32_e32 v214, v73
	v_mov_b32_e32 v216, v74
	v_mov_b32_e32 v218, v75
	s_waitcnt lgkmcnt(0)
	v_pk_mul_f32 v[200:201], v[200:201], s[12:13]
	v_pk_mul_f32 v[214:215], v[214:215], s[12:13]
	v_pk_mul_f32 v[216:217], v[216:217], s[12:13]
	v_pk_mul_f32 v[218:219], v[218:219], s[12:13]
	v_add_f32_e32 v200, v200, v201
	v_add_f32_e32 v214, v214, v215
	v_add_f32_e32 v216, v216, v217
	v_add_f32_e32 v218, v218, v219
	v_cndmask_b32_e64 v206, v202, v200, s[14:15]
	v_cndmask_b32_e64 v205, v202, v214, s[16:17]
	v_cndmask_b32_e64 v208, v202, v216, s[20:21]
	v_cndmask_b32_e64 v207, v202, v218, s[22:23]
	v_add_u32_e32 v72, s76, v130
	v_mad_i32_i24 v118, v72, s58, v118
	ds_read_b128 v[72:75], v118
	ds_read_b128 v[184:187], v118 offset:64
	ds_read_b128 v[188:191], v118 offset:128
	v_mov_b32_e32 v209, 0xf149f2ca
	v_mov_b32_e32 v210, 0xf149f2ca
	s_waitcnt lgkmcnt(2)
	v_mfma_f32_16x16x32_bf16 v[72:75], v[72:75], v[24:27], 0
	s_waitcnt lgkmcnt(1)
	v_mfma_f32_16x16x32_bf16 v[72:75], v[184:187], v[28:31], v[72:75]
	ds_read_b128 v[184:187], v118 offset:192
	s_waitcnt lgkmcnt(1)
	v_mfma_f32_16x16x32_bf16 v[72:75], v[188:191], v[36:39], v[72:75]
	s_waitcnt lgkmcnt(0)
	v_mfma_f32_16x16x32_bf16 v[72:75], v[184:187], v[40:43], v[72:75]
	ds_read_b32 v201, v223 offset:1736
	ds_read_b32 v215, v224 offset:1736
	ds_read_b32 v217, v225 offset:1736
	ds_read_b32 v219, v226 offset:1736
	s_nop 4
	v_mov_b32_e32 v200, v72
	v_mov_b32_e32 v214, v73
	v_mov_b32_e32 v216, v74
	v_mov_b32_e32 v218, v75
	s_waitcnt lgkmcnt(0)
	v_pk_mul_f32 v[200:201], v[200:201], s[12:13]
	v_pk_mul_f32 v[214:215], v[214:215], s[12:13]
	v_pk_mul_f32 v[216:217], v[216:217], s[12:13]
	v_pk_mul_f32 v[218:219], v[218:219], s[12:13]
	v_add_f32_e32 v200, v200, v201
	v_add_f32_e32 v214, v214, v215
	v_add_f32_e32 v216, v216, v217
	v_add_f32_e32 v218, v218, v219
	v_cndmask_b32_e64 v210, v202, v200, s[24:25]
	v_cndmask_b32_e64 v209, v202, v214, s[26:27]
	v_cndmask_b32_e64 v212, v202, v216, s[36:37]
	v_cndmask_b32_e64 v211, v202, v218, s[0:1]
	s_lshl_b32 s14, s73, 7
	v_max3_f32 v72, v115, s63, v104
	v_max3_f32 v72, v72, v117, v116
	v_max3_f32 v72, v72, v120, v119
	v_max3_f32 v72, v72, v122, v121
	v_max3_f32 v72, v72, v128, v126
	v_max3_f32 v72, v72, v136, v135
	v_max3_f32 v72, v72, v138, v137
	v_max3_f32 v72, v72, v140, v139
	v_max3_f32 v72, v72, v142, v141
	v_max3_f32 v72, v72, v144, v143
	v_max3_f32 v72, v72, v146, v145
	v_max3_f32 v72, v72, v148, v147
	v_max3_f32 v72, v72, v150, v149
	v_max3_f32 v72, v72, v152, v151
	v_max3_f32 v72, v72, v154, v153
	v_max3_f32 v72, v72, v156, v155
	v_max3_f32 v72, v72, v158, v157
	v_max3_f32 v72, v72, v160, v159
	v_max3_f32 v72, v72, v162, v161
	v_max3_f32 v72, v72, v164, v163
	v_max3_f32 v72, v72, v166, v165
	v_max3_f32 v72, v72, v168, v167
	v_max3_f32 v72, v72, v170, v169
	v_max3_f32 v72, v72, v172, v171
	v_max3_f32 v72, v72, v174, v173
	v_max3_f32 v72, v72, v176, v175
	v_max3_f32 v72, v72, v183, v181
	v_max3_f32 v72, v72, v204, v203
	v_and_b32_e32 v74, 64, v107
	v_max3_f32 v72, v72, v206, v205
	v_xor_b32_e32 v73, 16, v107
	v_add_u32_e32 v74, 64, v74
	v_max3_f32 v72, v72, v208, v207
	v_cmp_lt_i32_e32 vcc, v73, v74
	v_max3_f32 v72, v72, v210, v209
	v_max3_f32 v72, v72, v212, v211
	v_cndmask_b32_e32 v73, v107, v73, vcc
	v_lshlrev_b32_e32 v213, 2, v73
	ds_bpermute_b32 v73, v213, v72
	s_waitcnt lgkmcnt(0)
	s_barrier
; template <int L>
; __device__ __forceinline__ void layer_body(const Args& args, LAS unsigned char* lds, const int wave, const int G, const int gw, const int NGW, const int lo, const int hi,
;                                            unsigned char* const ws_kernel, const XcdBarrier& bar, int& pid) {
;     ...
;                     mx = fmaxf(mx, __shfl_xor(mx, 16)); mx = fmaxf(mx, __shfl_xor(mx, 32));
;                     float sum = 0.f;
; #pragma unroll
;                     for (int t = 0; t < 16; ++t)
; #pragma unroll
;                         for (int j = 0; j < 4; ++j) { sc[t][j] = __builtin_amdgcn_exp2f(sc[t][j] - mx); sum += sc[t][j]; }
;                     sum += __shfl_xor(sum, 16); sum += __shfl_xor(sum, 32);
	s_add_i32 s40, s40, s86
	v_max_f32_e32 v73, v73, v73
	v_max_f32_e32 v72, v72, v73
	v_xor_b32_e32 v73, 32, v107
	v_cmp_lt_i32_e32 vcc, v73, v74
	s_cmp_ge_i32 s40, s41
	s_cselect_b64 s[0:1], -1, 0
	v_cndmask_b32_e32 v73, v107, v73, vcc
	v_lshlrev_b32_e32 v214, 2, v73
	ds_bpermute_b32 v73, v214, v72
	s_and_b64 vcc, exec, s[0:1]
	s_waitcnt lgkmcnt(0)
	v_max_f32_e32 v73, v73, v73
	v_max_f32_e32 v215, v72, v73
	v_sub_f32_e32 v72, v115, v215
	v_exp_f32_e32 v190, v72
	v_sub_f32_e32 v72, v104, v215
	v_exp_f32_e32 v198, v72
	v_sub_f32_e32 v72, v117, v215
	v_exp_f32_e32 v194, v72
	v_sub_f32_e32 v72, v116, v215
	v_exp_f32_e32 v200, v72
	v_sub_f32_e32 v72, v120, v215
	v_sub_f32_e32 v104, v209, v215
	v_exp_f32_e32 v196, v72
	v_sub_f32_e32 v72, v119, v215
	v_exp_f32_e32 v119, v104
	v_sub_f32_e32 v104, v212, v215
	v_exp_f32_e32 v201, v72
	v_sub_f32_e32 v72, v122, v215
	v_exp_f32_e32 v116, v104
	v_sub_f32_e32 v104, v211, v215
	v_exp_f32_e32 v199, v72
	v_sub_f32_e32 v72, v121, v215
	v_exp_f32_e32 v121, v104
	v_add_f32_e32 v104, 0, v190
	v_add_f32_e32 v104, v198, v104
	v_add_f32_e32 v104, v194, v104
	v_exp_f32_e32 v202, v72
	v_sub_f32_e32 v72, v128, v215
	v_add_f32_e32 v104, v200, v104
	v_exp_f32_e32 v180, v72
	v_sub_f32_e32 v72, v126, v215
	v_add_f32_e32 v104, v196, v104
	v_exp_f32_e32 v191, v72
	v_sub_f32_e32 v72, v136, v215
	v_add_f32_e32 v104, v201, v104
	v_exp_f32_e32 v186, v72
	v_sub_f32_e32 v72, v135, v215
	v_add_f32_e32 v104, v199, v104
	v_exp_f32_e32 v193, v72
	v_sub_f32_e32 v72, v138, v215
	v_add_f32_e32 v104, v202, v104
	v_exp_f32_e32 v188, v72
	v_sub_f32_e32 v72, v137, v215
	v_add_f32_e32 v104, v180, v104
	v_exp_f32_e32 v195, v72
	v_sub_f32_e32 v72, v140, v215
	v_add_f32_e32 v104, v191, v104
	v_exp_f32_e32 v192, v72
	v_sub_f32_e32 v72, v139, v215
	v_add_f32_e32 v104, v186, v104
	v_exp_f32_e32 v197, v72
	v_sub_f32_e32 v72, v142, v215
	v_add_f32_e32 v104, v193, v104
	v_exp_f32_e32 v177, v72
	v_sub_f32_e32 v72, v141, v215
	v_add_f32_e32 v104, v188, v104
	v_exp_f32_e32 v182, v72
	v_sub_f32_e32 v72, v144, v215
	v_add_f32_e32 v104, v195, v104
	v_exp_f32_e32 v178, v72
	v_sub_f32_e32 v72, v143, v215
	v_add_f32_e32 v104, v192, v104
	v_exp_f32_e32 v185, v72
	v_sub_f32_e32 v72, v146, v215
	v_add_f32_e32 v104, v197, v104
	v_exp_f32_e32 v179, v72
	v_sub_f32_e32 v72, v145, v215
	v_add_f32_e32 v104, v177, v104
	v_exp_f32_e32 v187, v72
	v_sub_f32_e32 v72, v148, v215
	v_add_f32_e32 v104, v182, v104
	v_exp_f32_e32 v184, v72
	v_sub_f32_e32 v72, v147, v215
	v_add_f32_e32 v104, v178, v104
	v_exp_f32_e32 v189, v72
	v_sub_f32_e32 v72, v150, v215
	v_add_f32_e32 v104, v185, v104
	v_exp_f32_e32 v138, v72
	v_sub_f32_e32 v72, v149, v215
	v_add_f32_e32 v104, v179, v104
	v_exp_f32_e32 v146, v72
	v_sub_f32_e32 v72, v152, v215
	v_add_f32_e32 v104, v187, v104
	v_exp_f32_e32 v142, v72
	v_sub_f32_e32 v72, v151, v215
	v_add_f32_e32 v104, v184, v104
	v_exp_f32_e32 v148, v72
	v_sub_f32_e32 v72, v154, v215
	v_add_f32_e32 v104, v189, v104
	v_exp_f32_e32 v144, v72
	v_sub_f32_e32 v72, v153, v215
	v_add_f32_e32 v104, v138, v104
	v_exp_f32_e32 v150, v72
	v_sub_f32_e32 v72, v156, v215
	v_add_f32_e32 v104, v146, v104
	v_exp_f32_e32 v147, v72
	v_sub_f32_e32 v72, v155, v215
	v_add_f32_e32 v104, v142, v104
	v_exp_f32_e32 v152, v72
	v_sub_f32_e32 v72, v158, v215
	v_add_f32_e32 v104, v148, v104
	v_exp_f32_e32 v130, v72
	v_sub_f32_e32 v72, v157, v215
	v_add_f32_e32 v104, v144, v104
	v_exp_f32_e32 v139, v72
	v_sub_f32_e32 v72, v160, v215
	v_add_f32_e32 v104, v150, v104
	v_exp_f32_e32 v134, v72
	v_sub_f32_e32 v72, v159, v215
	v_add_f32_e32 v104, v147, v104
	v_exp_f32_e32 v141, v72
	v_sub_f32_e32 v72, v162, v215
	v_add_f32_e32 v104, v152, v104
	v_exp_f32_e32 v136, v72
	v_sub_f32_e32 v72, v161, v215
	v_add_f32_e32 v104, v130, v104
	v_exp_f32_e32 v143, v72
	v_sub_f32_e32 v72, v164, v215
	v_add_f32_e32 v104, v139, v104
	v_exp_f32_e32 v140, v72
	v_sub_f32_e32 v72, v163, v215
	v_add_f32_e32 v104, v134, v104
	v_exp_f32_e32 v145, v72
	v_sub_f32_e32 v72, v166, v215
	v_add_f32_e32 v104, v141, v104
	v_exp_f32_e32 v122, v72
	v_sub_f32_e32 v72, v165, v215
	v_add_f32_e32 v104, v136, v104
	v_exp_f32_e32 v131, v72
	v_sub_f32_e32 v72, v168, v215
	v_add_f32_e32 v104, v143, v104
	v_exp_f32_e32 v126, v72
	v_sub_f32_e32 v72, v167, v215
	v_add_f32_e32 v104, v140, v104
	v_exp_f32_e32 v133, v72
	v_sub_f32_e32 v72, v170, v215
	v_add_f32_e32 v104, v145, v104
	v_exp_f32_e32 v128, v72
	v_sub_f32_e32 v72, v169, v215
	v_add_f32_e32 v104, v122, v104
	v_exp_f32_e32 v135, v72
	v_sub_f32_e32 v72, v172, v215
	v_add_f32_e32 v104, v131, v104
	v_exp_f32_e32 v132, v72
	v_sub_f32_e32 v72, v171, v215
	v_add_f32_e32 v104, v126, v104
	v_exp_f32_e32 v137, v72
	v_sub_f32_e32 v72, v174, v215
	v_add_f32_e32 v104, v133, v104
	v_exp_f32_e32 v75, v72
	v_sub_f32_e32 v72, v173, v215
	v_add_f32_e32 v104, v128, v104
	v_exp_f32_e32 v123, v72
	v_sub_f32_e32 v72, v176, v215
	v_add_f32_e32 v104, v135, v104
	v_exp_f32_e32 v118, v72
	v_sub_f32_e32 v72, v175, v215
	v_add_f32_e32 v104, v132, v104
	v_exp_f32_e32 v125, v72
	v_sub_f32_e32 v72, v183, v215
	v_add_f32_e32 v104, v137, v104
	v_exp_f32_e32 v120, v72
	v_sub_f32_e32 v72, v181, v215
	v_add_f32_e32 v104, v75, v104
	v_exp_f32_e32 v127, v72
	v_sub_f32_e32 v72, v204, v215
	v_add_f32_e32 v104, v123, v104
	v_exp_f32_e32 v124, v72
	v_sub_f32_e32 v72, v203, v215
	v_add_f32_e32 v104, v118, v104
	v_exp_f32_e32 v129, v72
	v_sub_f32_e32 v72, v206, v215
	v_add_f32_e32 v104, v125, v104
	v_exp_f32_e32 v72, v72
	v_sub_f32_e32 v73, v205, v215
	v_add_f32_e32 v104, v120, v104
	v_exp_f32_e32 v115, v73
	v_sub_f32_e32 v73, v208, v215
	v_add_f32_e32 v104, v127, v104
	v_exp_f32_e32 v73, v73
	v_sub_f32_e32 v74, v207, v215
	v_add_f32_e32 v104, v124, v104
	v_exp_f32_e32 v117, v74
	v_sub_f32_e32 v74, v210, v215
	v_add_f32_e32 v104, v129, v104
	v_exp_f32_e32 v74, v74
	v_add_f32_e32 v104, v72, v104
	v_add_f32_e32 v104, v115, v104
	v_add_f32_e32 v104, v73, v104
	v_add_f32_e32 v104, v117, v104
	v_add_f32_e32 v104, v74, v104
	v_add_f32_e32 v104, v119, v104
	v_add_f32_e32 v104, v116, v104
	v_add_f32_e32 v104, v121, v104
	ds_bpermute_b32 v149, v213, v104
	v_lshlrev_b32_e32 v153, 2, v76
	v_and_b32_e32 v153, 12, v153
	s_waitcnt lgkmcnt(0)
; #define LAS __attribute__((address_space(3)))
; __device__ __forceinline__ unsigned pk2(float lo, float hi) { return f2bf(lo) | (f2bf(hi) << 16); }
; template <int L>
; __device__ __forceinline__ void layer_body(const Args& args, LAS unsigned char* lds, const int wave, const int G, const int gw, const int NGW, const int lo, const int hi,
;                                            unsigned char* const ws_kernel, const XcdBarrier& bar, int& pid) {
;     ...
;                     sum += __shfl_xor(sum, 16); sum += __shfl_xor(sum, 32);
;                     bf16x8 pbf[8];
; #pragma unroll
;                     for (int s = 0; s < 8; ++s) { const f32x4 p0 = sc[2 * s], p1 = sc[2 * s + 1]; v4u w; w.x = pk2(p0[0], p0[1]); w.y = pk2(p0[2], p0[3]); w.z = pk2(p1[0], p1[1]); w.w = pk2(p1[2], p1[3]); pbf[s] = __builtin_bit_cast(bf16x8, w); }
;                     __syncthreads();
; #pragma unroll
;                     for (int i = 0; i < 14; ++i) { const int kid = skey + 32 * i; *(LAS v4u*)(size_t)(IMG + vimg_off(kid, sch)) = rst[i]; }
;                     __syncthreads();
;                     if (unit + GH < UEND) { NA_LOADROWS(unit + GH, rst, D); NA_LOADQ(unit + GH); }
	v_add_f32_e32 v149, v104, v149
	v_lshlrev_b32_e32 v104, 8, v76
	v_bfe_u32 v76, v76, 2, 2
	v_bitop3_b32 v76, v153, v112, v76 bitop3:0x36
	v_lshlrev_b32_e32 v76, 4, v76
	v_add3_u32 v76, v104, 0, v76
	ds_bpermute_b32 v151, v214, v149
	v_add_u32_e32 v104, 0x10000, v76
	s_waitcnt vmcnt(13)
	ds_write_b128 v76, v[4:7]
	s_waitcnt vmcnt(12)
	ds_write_b128 v76, v[0:3] offset:8192
	s_waitcnt vmcnt(11)
	ds_write_b128 v76, v[12:15] offset:16384
	s_waitcnt vmcnt(10)
	ds_write_b128 v76, v[8:11] offset:24576
	s_waitcnt vmcnt(9)
	ds_write_b128 v76, v[20:23] offset:32768
	s_waitcnt vmcnt(8)
	ds_write_b128 v76, v[16:19] offset:40960
	s_waitcnt vmcnt(7)
	ds_write_b128 v76, v[32:35] offset:49152
	s_waitcnt vmcnt(6)
	ds_write_b128 v76, v[44:47] offset:57344
	s_waitcnt vmcnt(5)
	ds_write_b128 v104, v[48:51]
	v_add_u32_e32 v104, 0x12000, v76
	s_waitcnt vmcnt(4)
	ds_write_b128 v104, v[52:55]
	v_add_u32_e32 v104, 0x14000, v76
	s_waitcnt vmcnt(3)
	ds_write_b128 v104, v[56:59]
	v_add_u32_e32 v104, 0x16000, v76
	s_waitcnt vmcnt(2)
	ds_write_b128 v104, v[60:63]
	v_add_u32_e32 v104, 0x18000, v76
	v_add_u32_e32 v76, 0x1a000, v76
	s_waitcnt vmcnt(1)
	ds_write_b128 v104, v[64:67]
	s_waitcnt vmcnt(0)
	ds_write_b128 v76, v[68:71]
	s_waitcnt lgkmcnt(0)
	s_barrier
	s_cbranch_vccnz .LBB0_3408
	s_add_i32 s16, s52, s53
	s_and_b32 s20, s16, 28
	s_add_i32 s22, s56, s57
	v_sub_u32_e64 v1, s20, 1 clamp
	s_and_b32 s16, s22, 0x780
	v_lshlrev_b32_e32 v0, 3, v112
	s_and_b32 s15, s40, 1
	s_max_u32 s21, s20, 4
	v_min_u32_e32 v1, 24, v1
	s_lshl_b32 s23, s16, 1
	s_add_u32 s16, s48, s23
	v_lshlrev_b32_e32 v104, 1, v0
	v_subrev_u32_e32 v0, s21, v1
	s_addc_u32 s17, s49, 0
	v_add_u32_e32 v31, 11, v0
	v_sub_u32_e64 v30, s20, 4 clamp
	v_lshl_add_u64 v[24:25], s[16:17], 0, v[104:105]
	s_and_b32 s21, s22, 0xfffff800
	s_mul_i32 s16, s15, 24
	v_min_i32_e32 v0, v77, v31
	v_min_i32_e32 v2, v79, v31
	v_min_i32_e32 v8, v81, v31
	v_min_i32_e32 v10, v83, v31
	v_min_i32_e32 v16, v85, v31
	v_min_i32_e32 v18, v87, v31
	v_min_i32_e32 v26, v89, v31
	v_min_i32_e32 v28, v91, v31
	s_or_b32 s22, s21, s16
	v_add_lshl_u32 v0, v0, v30, 6
	v_add_lshl_u32 v2, v2, v30, 6
	v_add_lshl_u32 v8, v8, v30, 6
	v_add_lshl_u32 v10, v10, v30, 6
	v_add_lshl_u32 v16, v16, v30, 6
	v_add_lshl_u32 v18, v18, v30, 6
	v_add_lshl_u32 v26, v26, v30, 6
	v_add_lshl_u32 v28, v28, v30, 6
	v_add3_u32 v0, v78, s22, v0
	v_add3_u32 v2, v80, s22, v2
	v_add3_u32 v8, v82, s22, v8
	v_add3_u32 v10, v84, s22, v10
	v_add3_u32 v16, v86, s22, v16
	v_add3_u32 v18, v88, s22, v18
	v_add3_u32 v26, v90, s22, v26
	v_add3_u32 v28, v92, s22, v28
	v_mad_i64_i32 v[0:1], s[16:17], v0, s62, v[24:25]
	v_mad_i64_i32 v[2:3], s[16:17], v2, s62, v[24:25]
	v_mad_i64_i32 v[8:9], s[16:17], v8, s62, v[24:25]
	v_mad_i64_i32 v[10:11], s[16:17], v10, s62, v[24:25]
	v_mad_i64_i32 v[16:17], s[16:17], v16, s62, v[24:25]
	v_mad_i64_i32 v[18:19], s[16:17], v18, s62, v[24:25]
	v_mad_i64_i32 v[26:27], s[16:17], v26, s62, v[24:25]
	v_mad_i64_i32 v[28:29], s[16:17], v28, s62, v[24:25]
	global_load_dwordx4 v[4:7], v[0:1], off
	s_nop 0
	global_load_dwordx4 v[0:3], v[2:3], off
	s_nop 0
	global_load_dwordx4 v[12:15], v[8:9], off
	s_nop 0
	global_load_dwordx4 v[8:11], v[10:11], off
	s_nop 0
	global_load_dwordx4 v[20:23], v[16:17], off
	s_nop 0
	global_load_dwordx4 v[16:19], v[18:19], off
	s_nop 0
	global_load_dwordx4 v[32:35], v[26:27], off
	global_load_dwordx4 v[44:47], v[28:29], off
	v_min_i32_e32 v26, v93, v31
	v_min_i32_e32 v28, v95, v31
	v_add_lshl_u32 v26, v26, v30, 6
	v_add_lshl_u32 v28, v28, v30, 6
	v_add3_u32 v26, v94, s22, v26
	v_add3_u32 v28, v96, s22, v28
	v_mad_i64_i32 v[26:27], s[16:17], v26, s62, v[24:25]
	v_mad_i64_i32 v[28:29], s[16:17], v28, s62, v[24:25]
	global_load_dwordx4 v[48:51], v[26:27], off
	global_load_dwordx4 v[52:55], v[28:29], off
	v_min_i32_e32 v26, v97, v31
	v_min_i32_e32 v28, v100, v31
	v_add_lshl_u32 v26, v26, v30, 6
	v_add_lshl_u32 v28, v28, v30, 6
	v_add3_u32 v26, v98, s22, v26
	v_add3_u32 v28, v101, s22, v28
	v_mad_i64_i32 v[26:27], s[16:17], v26, s62, v[24:25]
	v_mad_i64_i32 v[28:29], s[16:17], v28, s62, v[24:25]
	global_load_dwordx4 v[56:59], v[26:27], off
	global_load_dwordx4 v[60:63], v[28:29], off
	v_min_i32_e32 v26, v102, v31
	v_min_i32_e32 v28, v113, v31
	v_add_lshl_u32 v26, v26, v30, 6
	v_add_lshl_u32 v28, v28, v30, 6
	v_add3_u32 v26, v103, s22, v26
	v_add3_u32 v28, v114, s22, v28
	v_mad_i64_i32 v[26:27], s[16:17], v26, s62, v[24:25]
	v_mad_i64_i32 v[24:25], s[16:17], v28, s62, v[24:25]
	s_add_u32 s16, s44, s23
	s_addc_u32 s17, s45, 0
	s_add_i32 s20, s20, s42
	s_lshl_b32 s20, s20, 6
	s_add_i32 s20, s20, s21
	s_lshl_b32 s15, s15, 5
	s_or_b32 s15, s20, s15
	s_or_b32 s15, s15, s43
	global_load_dwordx4 v[64:67], v[26:27], off
	global_load_dwordx4 v[68:71], v[24:25], off
	v_or_b32_e32 v26, s15, v112
	v_mov_b64_e32 v[24:25], s[16:17]
	v_mad_i64_i32 v[24:25], s[16:17], v26, s62, v[24:25]
	v_lshlrev_b32_e32 v104, 4, v99
	v_lshl_add_u64 v[40:41], v[24:25], 0, v[104:105]
	global_load_dwordx4 v[24:27], v[40:41], off
	global_load_dwordx4 v[28:31], v[40:41], off offset:64
	global_load_dwordx4 v[36:39], v[40:41], off offset:128
	s_nop 0
	global_load_dwordx4 v[40:43], v[40:41], off offset:192
	s_branch .LBB0_3408
